# SwiGLU epilogue with packed f32 ops; gemm_in epilogue row-ssq loads issued together (one wait instead of an 8-step ladder)
# speedup vs baseline: 1.0900x; 1.0027x over previous
; __device__ __forceinline__ int otid() { int t = (int)threadIdx.x; asm volatile("" : "+v"(t)); return t; }
; __device__ __forceinline__ unsigned cvt_pk_bf16(float lo, float hi) { unsigned r; asm volatile("v_cvt_pk_bf16_f32 %0, %1, %2" : "=v"(r) : "v"(lo), "v"(hi)); return r; }
; __device__ __forceinline__ float sigmoidf_(float x) { return 1.0f / (1.0f + __builtin_amdgcn_exp2f(-1.4426950408889634f * x)); }
;     __device__ __forceinline__ void operator()(const f32x4 (&acc)[2][2][4][2], const Unit& u, int wr, int wc, int fr, int fq) const {
;         { const int ln_ = otid() & 63; fr = ln_ & 15; fq = ln_ >> 4; }
;         const size_t rowb = (size_t)u.pm * BM + wr * 64 + fr; const int col0 = u.pn * HALF + wc * 32 + 8 * fq;
;         const float* bwp = bw + (size_t)(u.pm >> 4) * 5632 + u.pn * BM + wc * 32 + 8 * fq;
;         const f32x4 bg0 = *(const f32x4*)bwp, bg1 = *(const f32x4*)(bwp + 4), bu0 = *(const f32x4*)(bwp + HALF), bu1 = *(const f32x4*)(bwp + HALF + 4);
; #pragma unroll
;         for (int ai = 0; ai < 2; ++ai)
; #pragma unroll
;             for (int m = 0; m < 4; ++m) { const size_t row = rowb + ai * HALF + m * 16; const float r = __builtin_amdgcn_rsqf(ssq2[row] * (1.0f / 1024.0f) + RMS_EPS);
;                 f32x4 g0 = acc[ai][0][m][0] * r + bg0, g1 = acc[ai][0][m][1] * r + bg1; const f32x4 u0 = acc[ai][1][m][0] * r + bu0, u1 = acc[ai][1][m][1] * r + bu1;
; #pragma unroll
;                 for (int i = 0; i < 4; ++i) { g0[i] = g0[i] * sigmoidf_(g0[i]) * u0[i]; g1[i] = g1[i] * sigmoidf_(g1[i]) * u1[i]; }
;                 u32x4 w; w.x = cvt_pk_bf16(g0[0], g0[1]); w.y = cvt_pk_bf16(g0[2], g0[3]); w.z = cvt_pk_bf16(g1[0], g1[1]); w.w = cvt_pk_bf16(g1[2], g1[3]);
;                 *(u32x4*)(O + row * 2816 + col0) = w; }
.LBB0_33:
	s_ashr_i32 s35, s34, 31
	v_mov_b32_e32 v26, v221
	s_lshl_b64 s[38:39], s[34:35], 8
	s_add_u32 s15, s38, s55
	s_addc_u32 s13, s39, s59
	v_and_or_b32 v160, v26, 15, s15
	s_lshl_b32 s15, s63, 7
	v_lshrrev_b32_e32 v26, 1, v26
	s_or_b32 s15, s15, s56
	v_and_b32_e32 v26, 24, v26
	v_or_b32_e32 v162, s15, v26
	s_ashr_i32 s15, s34, 4
	s_mul_hi_i32 s34, s15, 0x5800
	s_mulk_i32 s15, 0x5800
	s_add_u32 s15, s53, s15
	s_addc_u32 s38, s54, s34
	s_lshl_b32 s34, s63, 8
	s_ashr_i32 s35, s34, 31
	s_lshl_b64 s[34:35], s[34:35], 2
	s_add_u32 s15, s15, s34
	v_mov_b32_e32 v161, s13
	s_addc_u32 s35, s38, s35
	s_add_u32 s34, s15, s62
	v_lshlrev_b64 v[158:159], 2, v[160:161]
	s_addc_u32 s35, s35, 0
	v_lshlrev_b32_e32 v30, 2, v26
	v_lshl_add_u64 v[156:157], s[8:9], 0, v[158:159]
	global_load_dwordx4 v[50:53], v30, s[34:35] offset:16
	global_load_dwordx4 v[54:57], v30, s[34:35]
	global_load_dwordx4 v[26:29], v30, s[34:35] offset:528
	s_nop 0
	global_load_dwordx4 v[30:33], v30, s[34:35] offset:512
	s_movk_i32 s15, 0x1600
	global_load_dword v161, v[156:157], off
	v_ashrrev_i32_e32 v163, 31, v162
	global_load_dword v233, v[156:157], off offset:0
	global_load_dword v234, v[156:157], off offset:64
	global_load_dword v235, v[156:157], off offset:128
	global_load_dword v236, v[156:157], off offset:192
	global_load_dword v237, v[156:157], off offset:512
	global_load_dword v238, v[156:157], off offset:576
	global_load_dword v239, v[156:157], off offset:640
	global_load_dword v240, v[156:157], off offset:704
	v_mul_u32_u24_e32 v252, 0x1600, v160
	v_lshl_add_u32 v252, v162, 1, v252
	s_mov_b32 s100, 0xbfb8aa3b
	s_mov_b32 s101, 0xbfb8aa3b
	s_waitcnt vmcnt(0)
	v_fmamk_f32 v242, v233, 0x3a800000, v231
	v_rsq_f32_e32 v242, v242
	s_nop 0
	v_pk_fma_f32 v[142:143], v[142:143], v[242:243], v[54:55] op_sel_hi:[1,0,1]
	v_pk_fma_f32 v[144:145], v[144:145], v[242:243], v[56:57] op_sel_hi:[1,0,1]
	v_pk_fma_f32 v[138:139], v[138:139], v[242:243], v[50:51] op_sel_hi:[1,0,1]
	v_pk_fma_f32 v[140:141], v[140:141], v[242:243], v[52:53] op_sel_hi:[1,0,1]
	v_pk_fma_f32 v[134:135], v[134:135], v[242:243], v[30:31] op_sel_hi:[1,0,1]
	v_pk_fma_f32 v[136:137], v[136:137], v[242:243], v[32:33] op_sel_hi:[1,0,1]
	v_pk_fma_f32 v[130:131], v[130:131], v[242:243], v[26:27] op_sel_hi:[1,0,1]
	v_pk_fma_f32 v[132:133], v[132:133], v[242:243], v[28:29] op_sel_hi:[1,0,1]
	v_pk_mul_f32 v[244:245], v[142:143], s[100:101]
	v_pk_mul_f32 v[246:247], v[144:145], s[100:101]
	v_pk_mul_f32 v[248:249], v[138:139], s[100:101]
	v_pk_mul_f32 v[250:251], v[140:141], s[100:101]
	v_exp_f32_e32 v244, v244
	v_exp_f32_e32 v245, v245
	v_exp_f32_e32 v246, v246
	v_exp_f32_e32 v247, v247
	v_exp_f32_e32 v248, v248
	v_exp_f32_e32 v249, v249
	v_exp_f32_e32 v250, v250
	v_exp_f32_e32 v251, v251
	v_pk_add_f32 v[244:245], v[244:245], 1.0 op_sel_hi:[1,0]
	v_pk_add_f32 v[246:247], v[246:247], 1.0 op_sel_hi:[1,0]
	v_pk_add_f32 v[248:249], v[248:249], 1.0 op_sel_hi:[1,0]
	v_pk_add_f32 v[250:251], v[250:251], 1.0 op_sel_hi:[1,0]
	v_rcp_f32_e32 v244, v244
	v_rcp_f32_e32 v245, v245
	v_rcp_f32_e32 v246, v246
	v_rcp_f32_e32 v247, v247
	v_rcp_f32_e32 v248, v248
	v_rcp_f32_e32 v249, v249
	v_rcp_f32_e32 v250, v250
	v_rcp_f32_e32 v251, v251
	v_pk_mul_f32 v[244:245], v[142:143], v[244:245]
	v_pk_mul_f32 v[246:247], v[144:145], v[246:247]
	v_pk_mul_f32 v[248:249], v[138:139], v[248:249]
	v_pk_mul_f32 v[250:251], v[140:141], v[250:251]
	v_pk_mul_f32 v[244:245], v[134:135], v[244:245]
	v_pk_mul_f32 v[246:247], v[136:137], v[246:247]
	v_pk_mul_f32 v[248:249], v[130:131], v[248:249]
	v_pk_mul_f32 v[250:251], v[132:133], v[250:251]
	v_cvt_pk_bf16_f32 v156, v244, v245
	v_cvt_pk_bf16_f32 v157, v246, v247
	v_cvt_pk_bf16_f32 v158, v248, v249
	v_cvt_pk_bf16_f32 v159, v250, v251
	global_store_dwordx4 v252, v[156:159], s[6:7]
	v_add_u32_e32 v252, 0x16000, v252
	v_fmamk_f32 v242, v234, 0x3a800000, v231
	v_rsq_f32_e32 v242, v242
	s_nop 0
	v_pk_fma_f32 v[126:127], v[126:127], v[242:243], v[54:55] op_sel_hi:[1,0,1]
	v_pk_fma_f32 v[128:129], v[128:129], v[242:243], v[56:57] op_sel_hi:[1,0,1]
	v_pk_fma_f32 v[122:123], v[122:123], v[242:243], v[50:51] op_sel_hi:[1,0,1]
	v_pk_fma_f32 v[124:125], v[124:125], v[242:243], v[52:53] op_sel_hi:[1,0,1]
	v_pk_fma_f32 v[118:119], v[118:119], v[242:243], v[30:31] op_sel_hi:[1,0,1]
	v_pk_fma_f32 v[120:121], v[120:121], v[242:243], v[32:33] op_sel_hi:[1,0,1]
	v_pk_fma_f32 v[114:115], v[114:115], v[242:243], v[26:27] op_sel_hi:[1,0,1]
	v_pk_fma_f32 v[116:117], v[116:117], v[242:243], v[28:29] op_sel_hi:[1,0,1]
	v_pk_mul_f32 v[244:245], v[126:127], s[100:101]
	v_pk_mul_f32 v[246:247], v[128:129], s[100:101]
	v_pk_mul_f32 v[248:249], v[122:123], s[100:101]
	v_pk_mul_f32 v[250:251], v[124:125], s[100:101]
	v_exp_f32_e32 v244, v244
	v_exp_f32_e32 v245, v245
	v_exp_f32_e32 v246, v246
	v_exp_f32_e32 v247, v247
	v_exp_f32_e32 v248, v248
	v_exp_f32_e32 v249, v249
	v_exp_f32_e32 v250, v250
	v_exp_f32_e32 v251, v251
	v_pk_add_f32 v[244:245], v[244:245], 1.0 op_sel_hi:[1,0]
	v_pk_add_f32 v[246:247], v[246:247], 1.0 op_sel_hi:[1,0]
	v_pk_add_f32 v[248:249], v[248:249], 1.0 op_sel_hi:[1,0]
	v_pk_add_f32 v[250:251], v[250:251], 1.0 op_sel_hi:[1,0]
	v_rcp_f32_e32 v244, v244
	v_rcp_f32_e32 v245, v245
	v_rcp_f32_e32 v246, v246
	v_rcp_f32_e32 v247, v247
	v_rcp_f32_e32 v248, v248
	v_rcp_f32_e32 v249, v249
	v_rcp_f32_e32 v250, v250
	v_rcp_f32_e32 v251, v251
	v_pk_mul_f32 v[244:245], v[126:127], v[244:245]
	v_pk_mul_f32 v[246:247], v[128:129], v[246:247]
	v_pk_mul_f32 v[248:249], v[122:123], v[248:249]
	v_pk_mul_f32 v[250:251], v[124:125], v[250:251]
	v_pk_mul_f32 v[244:245], v[118:119], v[244:245]
	v_pk_mul_f32 v[246:247], v[120:121], v[246:247]
; __device__ __forceinline__ unsigned cvt_pk_bf16(float lo, float hi) { unsigned r; asm volatile("v_cvt_pk_bf16_f32 %0, %1, %2" : "=v"(r) : "v"(lo), "v"(hi)); return r; }
; __device__ __forceinline__ float sigmoidf_(float x) { return 1.0f / (1.0f + __builtin_amdgcn_exp2f(-1.4426950408889634f * x)); }
;     __device__ __forceinline__ void operator()(const f32x4 (&acc)[2][2][4][2], const Unit& u, int wr, int wc, int fr, int fq) const {
;     ...
;             for (int m = 0; m < 4; ++m) { const size_t row = rowb + ai * HALF + m * 16; const float r = __builtin_amdgcn_rsqf(ssq2[row] * (1.0f / 1024.0f) + RMS_EPS);
;                 f32x4 g0 = acc[ai][0][m][0] * r + bg0, g1 = acc[ai][0][m][1] * r + bg1; const f32x4 u0 = acc[ai][1][m][0] * r + bu0, u1 = acc[ai][1][m][1] * r + bu1;
; #pragma unroll
;                 for (int i = 0; i < 4; ++i) { g0[i] = g0[i] * sigmoidf_(g0[i]) * u0[i]; g1[i] = g1[i] * sigmoidf_(g1[i]) * u1[i]; }
;                 u32x4 w; w.x = cvt_pk_bf16(g0[0], g0[1]); w.y = cvt_pk_bf16(g0[2], g0[3]); w.z = cvt_pk_bf16(g1[0], g1[1]); w.w = cvt_pk_bf16(g1[2], g1[3]);
;                 *(u32x4*)(O + row * 2816 + col0) = w; }
	v_pk_mul_f32 v[248:249], v[114:115], v[248:249]
	v_pk_mul_f32 v[250:251], v[116:117], v[250:251]
	v_cvt_pk_bf16_f32 v156, v244, v245
	v_cvt_pk_bf16_f32 v157, v246, v247
	v_cvt_pk_bf16_f32 v158, v248, v249
	v_cvt_pk_bf16_f32 v159, v250, v251
	global_store_dwordx4 v252, v[156:159], s[6:7]
	v_add_u32_e32 v252, 0x16000, v252
	v_fmamk_f32 v242, v235, 0x3a800000, v231
	v_rsq_f32_e32 v242, v242
	s_nop 0
	v_pk_fma_f32 v[110:111], v[110:111], v[242:243], v[54:55] op_sel_hi:[1,0,1]
	v_pk_fma_f32 v[112:113], v[112:113], v[242:243], v[56:57] op_sel_hi:[1,0,1]
	v_pk_fma_f32 v[106:107], v[106:107], v[242:243], v[50:51] op_sel_hi:[1,0,1]
	v_pk_fma_f32 v[108:109], v[108:109], v[242:243], v[52:53] op_sel_hi:[1,0,1]
	v_pk_fma_f32 v[102:103], v[102:103], v[242:243], v[30:31] op_sel_hi:[1,0,1]
	v_pk_fma_f32 v[104:105], v[104:105], v[242:243], v[32:33] op_sel_hi:[1,0,1]
	v_pk_fma_f32 v[98:99], v[98:99], v[242:243], v[26:27] op_sel_hi:[1,0,1]
	v_pk_fma_f32 v[100:101], v[100:101], v[242:243], v[28:29] op_sel_hi:[1,0,1]
	v_pk_mul_f32 v[244:245], v[110:111], s[100:101]
	v_pk_mul_f32 v[246:247], v[112:113], s[100:101]
	v_pk_mul_f32 v[248:249], v[106:107], s[100:101]
	v_pk_mul_f32 v[250:251], v[108:109], s[100:101]
	v_exp_f32_e32 v244, v244
	v_exp_f32_e32 v245, v245
	v_exp_f32_e32 v246, v246
	v_exp_f32_e32 v247, v247
	v_exp_f32_e32 v248, v248
	v_exp_f32_e32 v249, v249
	v_exp_f32_e32 v250, v250
	v_exp_f32_e32 v251, v251
	v_pk_add_f32 v[244:245], v[244:245], 1.0 op_sel_hi:[1,0]
	v_pk_add_f32 v[246:247], v[246:247], 1.0 op_sel_hi:[1,0]
	v_pk_add_f32 v[248:249], v[248:249], 1.0 op_sel_hi:[1,0]
	v_pk_add_f32 v[250:251], v[250:251], 1.0 op_sel_hi:[1,0]
	v_rcp_f32_e32 v244, v244
	v_rcp_f32_e32 v245, v245
	v_rcp_f32_e32 v246, v246
	v_rcp_f32_e32 v247, v247
	v_rcp_f32_e32 v248, v248
	v_rcp_f32_e32 v249, v249
	v_rcp_f32_e32 v250, v250
	v_rcp_f32_e32 v251, v251
	v_pk_mul_f32 v[244:245], v[110:111], v[244:245]
	v_pk_mul_f32 v[246:247], v[112:113], v[246:247]
	v_pk_mul_f32 v[248:249], v[106:107], v[248:249]
	v_pk_mul_f32 v[250:251], v[108:109], v[250:251]
	v_pk_mul_f32 v[244:245], v[102:103], v[244:245]
	v_pk_mul_f32 v[246:247], v[104:105], v[246:247]
	v_pk_mul_f32 v[248:249], v[98:99], v[248:249]
	v_pk_mul_f32 v[250:251], v[100:101], v[250:251]
	v_cvt_pk_bf16_f32 v156, v244, v245
	v_cvt_pk_bf16_f32 v157, v246, v247
	v_cvt_pk_bf16_f32 v158, v248, v249
	v_cvt_pk_bf16_f32 v159, v250, v251
	global_store_dwordx4 v252, v[156:159], s[6:7]
	v_add_u32_e32 v252, 0x16000, v252
	v_fmamk_f32 v242, v236, 0x3a800000, v231
	v_rsq_f32_e32 v242, v242
	s_nop 0
	v_pk_fma_f32 v[94:95], v[94:95], v[242:243], v[54:55] op_sel_hi:[1,0,1]
	v_pk_fma_f32 v[96:97], v[96:97], v[242:243], v[56:57] op_sel_hi:[1,0,1]
	v_pk_fma_f32 v[90:91], v[90:91], v[242:243], v[50:51] op_sel_hi:[1,0,1]
	v_pk_fma_f32 v[92:93], v[92:93], v[242:243], v[52:53] op_sel_hi:[1,0,1]
	v_pk_fma_f32 v[86:87], v[86:87], v[242:243], v[30:31] op_sel_hi:[1,0,1]
	v_pk_fma_f32 v[88:89], v[88:89], v[242:243], v[32:33] op_sel_hi:[1,0,1]
	v_pk_fma_f32 v[82:83], v[82:83], v[242:243], v[26:27] op_sel_hi:[1,0,1]
	v_pk_fma_f32 v[84:85], v[84:85], v[242:243], v[28:29] op_sel_hi:[1,0,1]
	v_pk_mul_f32 v[244:245], v[94:95], s[100:101]
	v_pk_mul_f32 v[246:247], v[96:97], s[100:101]
	v_pk_mul_f32 v[248:249], v[90:91], s[100:101]
	v_pk_mul_f32 v[250:251], v[92:93], s[100:101]
	v_exp_f32_e32 v244, v244
	v_exp_f32_e32 v245, v245
	v_exp_f32_e32 v246, v246
	v_exp_f32_e32 v247, v247
	v_exp_f32_e32 v248, v248
	v_exp_f32_e32 v249, v249
	v_exp_f32_e32 v250, v250
	v_exp_f32_e32 v251, v251
	v_pk_add_f32 v[244:245], v[244:245], 1.0 op_sel_hi:[1,0]
	v_pk_add_f32 v[246:247], v[246:247], 1.0 op_sel_hi:[1,0]
	v_pk_add_f32 v[248:249], v[248:249], 1.0 op_sel_hi:[1,0]
	v_pk_add_f32 v[250:251], v[250:251], 1.0 op_sel_hi:[1,0]
	v_rcp_f32_e32 v244, v244
	v_rcp_f32_e32 v245, v245
	v_rcp_f32_e32 v246, v246
	v_rcp_f32_e32 v247, v247
	v_rcp_f32_e32 v248, v248
	v_rcp_f32_e32 v249, v249
	v_rcp_f32_e32 v250, v250
	v_rcp_f32_e32 v251, v251
	v_pk_mul_f32 v[244:245], v[94:95], v[244:245]
	v_pk_mul_f32 v[246:247], v[96:97], v[246:247]
	v_pk_mul_f32 v[248:249], v[90:91], v[248:249]
	v_pk_mul_f32 v[250:251], v[92:93], v[250:251]
	v_pk_mul_f32 v[244:245], v[86:87], v[244:245]
	v_pk_mul_f32 v[246:247], v[88:89], v[246:247]
	v_pk_mul_f32 v[248:249], v[82:83], v[248:249]
	v_pk_mul_f32 v[250:251], v[84:85], v[250:251]
	v_cvt_pk_bf16_f32 v156, v244, v245
	v_cvt_pk_bf16_f32 v157, v246, v247
	v_cvt_pk_bf16_f32 v158, v248, v249
	v_cvt_pk_bf16_f32 v159, v250, v251
	global_store_dwordx4 v252, v[156:159], s[6:7]
	v_add_u32_e32 v252, 0x6e000, v252
	v_fmamk_f32 v242, v237, 0x3a800000, v231
	v_rsq_f32_e32 v242, v242
	s_nop 0
	v_pk_fma_f32 v[78:79], v[78:79], v[242:243], v[54:55] op_sel_hi:[1,0,1]
	v_pk_fma_f32 v[80:81], v[80:81], v[242:243], v[56:57] op_sel_hi:[1,0,1]
	v_pk_fma_f32 v[74:75], v[74:75], v[242:243], v[50:51] op_sel_hi:[1,0,1]
	v_pk_fma_f32 v[76:77], v[76:77], v[242:243], v[52:53] op_sel_hi:[1,0,1]
	v_pk_fma_f32 v[70:71], v[70:71], v[242:243], v[30:31] op_sel_hi:[1,0,1]
	v_pk_fma_f32 v[72:73], v[72:73], v[242:243], v[32:33] op_sel_hi:[1,0,1]
	v_pk_fma_f32 v[62:63], v[62:63], v[242:243], v[26:27] op_sel_hi:[1,0,1]
	v_pk_fma_f32 v[64:65], v[64:65], v[242:243], v[28:29] op_sel_hi:[1,0,1]
	v_pk_mul_f32 v[244:245], v[78:79], s[100:101]
	v_pk_mul_f32 v[246:247], v[80:81], s[100:101]
	v_pk_mul_f32 v[248:249], v[74:75], s[100:101]
	v_pk_mul_f32 v[250:251], v[76:77], s[100:101]
	v_exp_f32_e32 v244, v244
	v_exp_f32_e32 v245, v245
	v_exp_f32_e32 v246, v246
	v_exp_f32_e32 v247, v247
	v_exp_f32_e32 v248, v248
	v_exp_f32_e32 v249, v249
	v_exp_f32_e32 v250, v250
	v_exp_f32_e32 v251, v251
; __device__ __forceinline__ unsigned cvt_pk_bf16(float lo, float hi) { unsigned r; asm volatile("v_cvt_pk_bf16_f32 %0, %1, %2" : "=v"(r) : "v"(lo), "v"(hi)); return r; }
; __device__ __forceinline__ float sigmoidf_(float x) { return 1.0f / (1.0f + __builtin_amdgcn_exp2f(-1.4426950408889634f * x)); }
;     __device__ __forceinline__ void operator()(const f32x4 (&acc)[2][2][4][2], const Unit& u, int wr, int wc, int fr, int fq) const {
;     ...
;             for (int m = 0; m < 4; ++m) { const size_t row = rowb + ai * HALF + m * 16; const float r = __builtin_amdgcn_rsqf(ssq2[row] * (1.0f / 1024.0f) + RMS_EPS);
;                 f32x4 g0 = acc[ai][0][m][0] * r + bg0, g1 = acc[ai][0][m][1] * r + bg1; const f32x4 u0 = acc[ai][1][m][0] * r + bu0, u1 = acc[ai][1][m][1] * r + bu1;
; #pragma unroll
;                 for (int i = 0; i < 4; ++i) { g0[i] = g0[i] * sigmoidf_(g0[i]) * u0[i]; g1[i] = g1[i] * sigmoidf_(g1[i]) * u1[i]; }
;                 u32x4 w; w.x = cvt_pk_bf16(g0[0], g0[1]); w.y = cvt_pk_bf16(g0[2], g0[3]); w.z = cvt_pk_bf16(g1[0], g1[1]); w.w = cvt_pk_bf16(g1[2], g1[3]);
;                 *(u32x4*)(O + row * 2816 + col0) = w; }
	v_pk_add_f32 v[244:245], v[244:245], 1.0 op_sel_hi:[1,0]
	v_pk_add_f32 v[246:247], v[246:247], 1.0 op_sel_hi:[1,0]
	v_pk_add_f32 v[248:249], v[248:249], 1.0 op_sel_hi:[1,0]
	v_pk_add_f32 v[250:251], v[250:251], 1.0 op_sel_hi:[1,0]
	v_rcp_f32_e32 v244, v244
	v_rcp_f32_e32 v245, v245
	v_rcp_f32_e32 v246, v246
	v_rcp_f32_e32 v247, v247
	v_rcp_f32_e32 v248, v248
	v_rcp_f32_e32 v249, v249
	v_rcp_f32_e32 v250, v250
	v_rcp_f32_e32 v251, v251
	v_pk_mul_f32 v[244:245], v[78:79], v[244:245]
	v_pk_mul_f32 v[246:247], v[80:81], v[246:247]
	v_pk_mul_f32 v[248:249], v[74:75], v[248:249]
	v_pk_mul_f32 v[250:251], v[76:77], v[250:251]
	v_pk_mul_f32 v[244:245], v[70:71], v[244:245]
	v_pk_mul_f32 v[246:247], v[72:73], v[246:247]
	v_pk_mul_f32 v[248:249], v[62:63], v[248:249]
	v_pk_mul_f32 v[250:251], v[64:65], v[250:251]
	v_cvt_pk_bf16_f32 v156, v244, v245
	v_cvt_pk_bf16_f32 v157, v246, v247
	v_cvt_pk_bf16_f32 v158, v248, v249
	v_cvt_pk_bf16_f32 v159, v250, v251
	global_store_dwordx4 v252, v[156:159], s[6:7]
	v_add_u32_e32 v252, 0x16000, v252
	v_fmamk_f32 v242, v238, 0x3a800000, v231
	v_rsq_f32_e32 v242, v242
	s_nop 0
	v_pk_fma_f32 v[66:67], v[66:67], v[242:243], v[54:55] op_sel_hi:[1,0,1]
	v_pk_fma_f32 v[68:69], v[68:69], v[242:243], v[56:57] op_sel_hi:[1,0,1]
	v_pk_fma_f32 v[58:59], v[58:59], v[242:243], v[50:51] op_sel_hi:[1,0,1]
	v_pk_fma_f32 v[60:61], v[60:61], v[242:243], v[52:53] op_sel_hi:[1,0,1]
	v_pk_fma_f32 v[46:47], v[46:47], v[242:243], v[30:31] op_sel_hi:[1,0,1]
	v_pk_fma_f32 v[48:49], v[48:49], v[242:243], v[32:33] op_sel_hi:[1,0,1]
	v_pk_fma_f32 v[38:39], v[38:39], v[242:243], v[26:27] op_sel_hi:[1,0,1]
	v_pk_fma_f32 v[40:41], v[40:41], v[242:243], v[28:29] op_sel_hi:[1,0,1]
	v_pk_mul_f32 v[244:245], v[66:67], s[100:101]
	v_pk_mul_f32 v[246:247], v[68:69], s[100:101]
	v_pk_mul_f32 v[248:249], v[58:59], s[100:101]
	v_pk_mul_f32 v[250:251], v[60:61], s[100:101]
	v_exp_f32_e32 v244, v244
	v_exp_f32_e32 v245, v245
	v_exp_f32_e32 v246, v246
	v_exp_f32_e32 v247, v247
	v_exp_f32_e32 v248, v248
	v_exp_f32_e32 v249, v249
	v_exp_f32_e32 v250, v250
	v_exp_f32_e32 v251, v251
	v_pk_add_f32 v[244:245], v[244:245], 1.0 op_sel_hi:[1,0]
	v_pk_add_f32 v[246:247], v[246:247], 1.0 op_sel_hi:[1,0]
	v_pk_add_f32 v[248:249], v[248:249], 1.0 op_sel_hi:[1,0]
	v_pk_add_f32 v[250:251], v[250:251], 1.0 op_sel_hi:[1,0]
	v_rcp_f32_e32 v244, v244
	v_rcp_f32_e32 v245, v245
	v_rcp_f32_e32 v246, v246
	v_rcp_f32_e32 v247, v247
	v_rcp_f32_e32 v248, v248
	v_rcp_f32_e32 v249, v249
	v_rcp_f32_e32 v250, v250
	v_rcp_f32_e32 v251, v251
	v_pk_mul_f32 v[244:245], v[66:67], v[244:245]
	v_pk_mul_f32 v[246:247], v[68:69], v[246:247]
	v_pk_mul_f32 v[248:249], v[58:59], v[248:249]
	v_pk_mul_f32 v[250:251], v[60:61], v[250:251]
	v_pk_mul_f32 v[244:245], v[46:47], v[244:245]
	v_pk_mul_f32 v[246:247], v[48:49], v[246:247]
	v_pk_mul_f32 v[248:249], v[38:39], v[248:249]
	v_pk_mul_f32 v[250:251], v[40:41], v[250:251]
	v_cvt_pk_bf16_f32 v156, v244, v245
	v_cvt_pk_bf16_f32 v157, v246, v247
	v_cvt_pk_bf16_f32 v158, v248, v249
	v_cvt_pk_bf16_f32 v159, v250, v251
	global_store_dwordx4 v252, v[156:159], s[6:7]
	v_add_u32_e32 v252, 0x16000, v252
	v_fmamk_f32 v242, v239, 0x3a800000, v231
	v_rsq_f32_e32 v242, v242
	s_nop 0
	v_pk_fma_f32 v[42:43], v[42:43], v[242:243], v[54:55] op_sel_hi:[1,0,1]
	v_pk_fma_f32 v[44:45], v[44:45], v[242:243], v[56:57] op_sel_hi:[1,0,1]
	v_pk_fma_f32 v[34:35], v[34:35], v[242:243], v[50:51] op_sel_hi:[1,0,1]
	v_pk_fma_f32 v[36:37], v[36:37], v[242:243], v[52:53] op_sel_hi:[1,0,1]
	v_pk_fma_f32 v[22:23], v[22:23], v[242:243], v[30:31] op_sel_hi:[1,0,1]
	v_pk_fma_f32 v[24:25], v[24:25], v[242:243], v[32:33] op_sel_hi:[1,0,1]
	v_pk_fma_f32 v[14:15], v[14:15], v[242:243], v[26:27] op_sel_hi:[1,0,1]
; __device__ __forceinline__ unsigned cvt_pk_bf16(float lo, float hi) { unsigned r; asm volatile("v_cvt_pk_bf16_f32 %0, %1, %2" : "=v"(r) : "v"(lo), "v"(hi)); return r; }
; __device__ __forceinline__ float sigmoidf_(float x) { return 1.0f / (1.0f + __builtin_amdgcn_exp2f(-1.4426950408889634f * x)); }
; #define PG8_BAR __builtin_amdgcn_s_barrier()
;     __device__ __forceinline__ void operator()(const f32x4 (&acc)[2][2][4][2], const Unit& u, int wr, int wc, int fr, int fq) const {
;     ...
;             for (int m = 0; m < 4; ++m) { const size_t row = rowb + ai * HALF + m * 16; const float r = __builtin_amdgcn_rsqf(ssq2[row] * (1.0f / 1024.0f) + RMS_EPS);
;                 f32x4 g0 = acc[ai][0][m][0] * r + bg0, g1 = acc[ai][0][m][1] * r + bg1; const f32x4 u0 = acc[ai][1][m][0] * r + bu0, u1 = acc[ai][1][m][1] * r + bu1;
; #pragma unroll
;                 for (int i = 0; i < 4; ++i) { g0[i] = g0[i] * sigmoidf_(g0[i]) * u0[i]; g1[i] = g1[i] * sigmoidf_(g1[i]) * u1[i]; }
;                 u32x4 w; w.x = cvt_pk_bf16(g0[0], g0[1]); w.y = cvt_pk_bf16(g0[2], g0[3]); w.z = cvt_pk_bf16(g1[0], g1[1]); w.w = cvt_pk_bf16(g1[2], g1[3]);
;                 *(u32x4*)(O + row * 2816 + col0) = w; }
; template <class Epi, class Sched, bool ALIGN_EPI = false, bool SP2 = false>
; __device__ __forceinline__ void gemm_phase(PG8_LAS unsigned char* lds, const Gemm g, const Sched& S, const Epi& E) {
;     ...
;         if (!has_next) break;
; #pragma unroll
;         for (int a = 0; a < 2; ++a)
; #pragma unroll
;             for (int b = 0; b < 2; ++b)
; #pragma unroll
;                 for (int m = 0; m < 4; ++m)
; #pragma unroll
;                     for (int n = 0; n < 2; ++n) acc[a][b][m][n] = (f32x4){0.f, 0.f, 0.f, 0.f};
;         cur = nxt; cA = nA; cB = nB; ++ui;
;         if constexpr (ALIGN_EPI) { if (wr == 1) PG8_BAR; }
	v_pk_fma_f32 v[16:17], v[16:17], v[242:243], v[28:29] op_sel_hi:[1,0,1]
	v_pk_mul_f32 v[244:245], v[42:43], s[100:101]
	v_pk_mul_f32 v[246:247], v[44:45], s[100:101]
	v_pk_mul_f32 v[248:249], v[34:35], s[100:101]
	v_pk_mul_f32 v[250:251], v[36:37], s[100:101]
	v_exp_f32_e32 v244, v244
	v_exp_f32_e32 v245, v245
	v_exp_f32_e32 v246, v246
	v_exp_f32_e32 v247, v247
	v_exp_f32_e32 v248, v248
	v_exp_f32_e32 v249, v249
	v_exp_f32_e32 v250, v250
	v_exp_f32_e32 v251, v251
	v_pk_add_f32 v[244:245], v[244:245], 1.0 op_sel_hi:[1,0]
	v_pk_add_f32 v[246:247], v[246:247], 1.0 op_sel_hi:[1,0]
	v_pk_add_f32 v[248:249], v[248:249], 1.0 op_sel_hi:[1,0]
	v_pk_add_f32 v[250:251], v[250:251], 1.0 op_sel_hi:[1,0]
	v_rcp_f32_e32 v244, v244
	v_rcp_f32_e32 v245, v245
	v_rcp_f32_e32 v246, v246
	v_rcp_f32_e32 v247, v247
	v_rcp_f32_e32 v248, v248
	v_rcp_f32_e32 v249, v249
	v_rcp_f32_e32 v250, v250
	v_rcp_f32_e32 v251, v251
	v_pk_mul_f32 v[244:245], v[42:43], v[244:245]
	v_pk_mul_f32 v[246:247], v[44:45], v[246:247]
	v_pk_mul_f32 v[248:249], v[34:35], v[248:249]
	v_pk_mul_f32 v[250:251], v[36:37], v[250:251]
	v_pk_mul_f32 v[244:245], v[22:23], v[244:245]
	v_pk_mul_f32 v[246:247], v[24:25], v[246:247]
	v_pk_mul_f32 v[248:249], v[14:15], v[248:249]
	v_pk_mul_f32 v[250:251], v[16:17], v[250:251]
	v_cvt_pk_bf16_f32 v156, v244, v245
	v_cvt_pk_bf16_f32 v157, v246, v247
	v_cvt_pk_bf16_f32 v158, v248, v249
	v_cvt_pk_bf16_f32 v159, v250, v251
	global_store_dwordx4 v252, v[156:159], s[6:7]
	v_add_u32_e32 v252, 0x16000, v252
	v_fmamk_f32 v242, v240, 0x3a800000, v231
	v_rsq_f32_e32 v242, v242
	s_nop 0
	v_pk_fma_f32 v[18:19], v[18:19], v[242:243], v[54:55] op_sel_hi:[1,0,1]
	v_pk_fma_f32 v[20:21], v[20:21], v[242:243], v[56:57] op_sel_hi:[1,0,1]
	v_pk_fma_f32 v[10:11], v[10:11], v[242:243], v[50:51] op_sel_hi:[1,0,1]
	v_pk_fma_f32 v[12:13], v[12:13], v[242:243], v[52:53] op_sel_hi:[1,0,1]
	v_pk_fma_f32 v[6:7], v[6:7], v[242:243], v[30:31] op_sel_hi:[1,0,1]
	v_pk_fma_f32 v[8:9], v[8:9], v[242:243], v[32:33] op_sel_hi:[1,0,1]
	v_pk_fma_f32 v[2:3], v[2:3], v[242:243], v[26:27] op_sel_hi:[1,0,1]
	v_pk_fma_f32 v[4:5], v[4:5], v[242:243], v[28:29] op_sel_hi:[1,0,1]
	v_pk_mul_f32 v[244:245], v[18:19], s[100:101]
	v_pk_mul_f32 v[246:247], v[20:21], s[100:101]
	v_pk_mul_f32 v[248:249], v[10:11], s[100:101]
	v_pk_mul_f32 v[250:251], v[12:13], s[100:101]
	v_exp_f32_e32 v244, v244
	v_exp_f32_e32 v245, v245
	v_exp_f32_e32 v246, v246
	v_exp_f32_e32 v247, v247
	v_exp_f32_e32 v248, v248
	v_exp_f32_e32 v249, v249
	v_exp_f32_e32 v250, v250
	v_exp_f32_e32 v251, v251
	v_pk_add_f32 v[244:245], v[244:245], 1.0 op_sel_hi:[1,0]
	v_pk_add_f32 v[246:247], v[246:247], 1.0 op_sel_hi:[1,0]
	v_pk_add_f32 v[248:249], v[248:249], 1.0 op_sel_hi:[1,0]
	v_pk_add_f32 v[250:251], v[250:251], 1.0 op_sel_hi:[1,0]
	v_rcp_f32_e32 v244, v244
	v_rcp_f32_e32 v245, v245
	v_rcp_f32_e32 v246, v246
	v_rcp_f32_e32 v247, v247
	v_rcp_f32_e32 v248, v248
	v_rcp_f32_e32 v249, v249
	v_rcp_f32_e32 v250, v250
	v_rcp_f32_e32 v251, v251
	v_pk_mul_f32 v[244:245], v[18:19], v[244:245]
	v_pk_mul_f32 v[246:247], v[20:21], v[246:247]
	v_pk_mul_f32 v[248:249], v[10:11], v[248:249]
	v_pk_mul_f32 v[250:251], v[12:13], v[250:251]
	v_pk_mul_f32 v[244:245], v[6:7], v[244:245]
	v_pk_mul_f32 v[246:247], v[8:9], v[246:247]
	v_pk_mul_f32 v[248:249], v[2:3], v[248:249]
	v_pk_mul_f32 v[250:251], v[4:5], v[250:251]
	v_cvt_pk_bf16_f32 v156, v244, v245
	v_cvt_pk_bf16_f32 v157, v246, v247
	v_cvt_pk_bf16_f32 v158, v248, v249
	v_cvt_pk_bf16_f32 v159, v250, v251
	global_store_dwordx4 v252, v[156:159], s[6:7]
	s_mov_b64 s[34:35], -1
	s_andn2_b64 vcc, exec, s[40:41]
	s_cbranch_vccnz .LBB0_26
	s_andn2_b64 vcc, exec, s[2:3]
	s_cbranch_vccnz .LBB0_25
	s_barrier
	s_branch .LBB0_25

; __device__ __forceinline__ float sigmoidf_(float x) { return 1.0f / (1.0f + __builtin_amdgcn_exp2f(-1.4426950408889634f * x)); }
; #define EPIIN_PACK(w, a, b) do { (w).x = cvt_pk_bf16((a)[0], (a)[1]); (w).y = cvt_pk_bf16((a)[2], (a)[3]); (w).z = cvt_pk_bf16((b)[0], (b)[1]); (w).w = cvt_pk_bf16((b)[2], (b)[3]); } while (0)
;     __device__ __forceinline__ void operator()(const f32x4 (&acc_)[2][2][4][2], const Unit& u, int wr, int wc, int fr, int fq) const {
;     ...
;         const int pn = u.pn; const size_t rowb = (size_t)u.pm * BM + wr * 64 + fr;
;         f32x4 bv[2][2]; float r8[2][4];
;         { const float* bwp = bw + (size_t)(u.pm >> 4) * 4096 + pn * BM + wc * 32 + fq * 8;
; #pragma unroll
;           for (int bj = 0; bj < 2; ++bj)
; #pragma unroll
;               for (int n = 0; n < 2; ++n) bv[bj][n] = *(const f32x4*)(bwp + bj * HALF + n * 4);
; #pragma unroll
;           for (int ai = 0; ai < 2; ++ai)
; #pragma unroll
;               for (int m = 0; m < 4; ++m) r8[ai][m] = __builtin_amdgcn_rsqf(ssq1[rowb + ai * HALF + m * 16] * (1.0f / 1024.0f) + RMS_EPS); }
;     ...
; #pragma unroll
;             for (int ai = 0; ai < 2; ++ai)
; #pragma unroll
;                 for (int m = 0; m < 4; ++m) { const size_t row = rowb + ai * HALF + m * 16;
; #pragma unroll
;                     for (int bj = 0; bj < 2; ++bj) { f32x4 a = EPIIN_VAL(ai, bj, m, 0), b = EPIIN_VAL(ai, bj, m, 1);
; #pragma unroll
;                         for (int i = 0; i < 4; ++i) { a[i] = sigmoidf_(a[i]); b[i] = sigmoidf_(b[i]); }
;                         u32x4 w; EPIIN_PACK(w, a, b);
;                         *(u32x4*)(GATES + row * 2048 + (pn - 8) * 256 + bj * HALF + wc * 32 + fq * 8) = w; } }
.LBB0_555:
	s_ashr_i32 s6, s2, 4
	s_ashr_i32 s7, s6, 31
	s_ashr_i32 s3, s2, 31
	s_lshl_b64 s[6:7], s[6:7], 14
	s_add_u32 s30, s12, s6
	s_addc_u32 s34, s13, s7
	s_lshl_b32 s68, s46, 8
	s_ashr_i32 s69, s68, 31
	s_lshl_b64 s[6:7], s[68:69], 2
	s_add_u32 s6, s30, s6
	s_addc_u32 s7, s34, s7
	s_lshl_b32 s30, s50, 2
	s_add_u32 s6, s6, s30
	s_addc_u32 s7, s7, 0
	s_lshl_b64 s[2:3], s[2:3], 8
	s_add_u32 s42, s2, s49
	v_mov_b32_e32 v0, v221
	s_addc_u32 s43, s3, s95
	v_mov_b32_e32 v159, s43
	v_bfe_u32 v165, v0, 4, 2
	v_and_or_b32 v158, v0, 15, s42
	v_lshlrev_b32_e32 v94, 5, v165
	v_lshl_add_u64 v[176:177], v[158:159], 2, s[16:17]
	global_load_dwordx4 v[106:109], v94, s[6:7] offset:16
	global_load_dwordx4 v[110:113], v94, s[6:7]
	global_load_dwordx4 v[90:93], v94, s[6:7] offset:528
	s_nop 0
	global_load_dwordx4 v[94:97], v94, s[6:7] offset:512
	v_lshlrev_b32_e32 v167, 3, v165
	global_load_dword v174, v[176:177], off
	global_load_dword v172, v[176:177], off offset:64
	global_load_dword v170, v[176:177], off offset:128
	global_load_dword v168, v[176:177], off offset:192
	global_load_dword v166, v[176:177], off offset:512
	global_load_dword v164, v[176:177], off offset:576
	global_load_dword v162, v[176:177], off offset:640
	global_load_dword v160, v[176:177], off offset:704
	s_mov_b64 s[2:3], -1
	s_cmp_gt_i32 s46, 1
	s_waitcnt vmcnt(0)
	v_fmamk_f32 v174, v174, 0x3a800000, v231
	v_fmamk_f32 v172, v172, 0x3a800000, v231
	v_fmamk_f32 v170, v170, 0x3a800000, v231
	v_fmamk_f32 v168, v168, 0x3a800000, v231
	v_fmamk_f32 v166, v166, 0x3a800000, v231
	v_fmamk_f32 v164, v164, 0x3a800000, v231
	v_fmamk_f32 v162, v162, 0x3a800000, v231
	v_fmamk_f32 v160, v160, 0x3a800000, v231
	v_rsq_f32_e32 v174, v174
	v_rsq_f32_e32 v172, v172
	v_rsq_f32_e32 v170, v170
	v_rsq_f32_e32 v168, v168
	v_rsq_f32_e32 v166, v166
	v_rsq_f32_e32 v164, v164
	v_rsq_f32_e32 v162, v162
	v_rsq_f32_e32 v160, v160
	s_nop 0
	s_cbranch_scc0 .LBB0_565
	s_cmp_gt_u32 s46, 5
	s_cbranch_scc0 .LBB0_562
	s_cmp_lt_u32 s46, 8
	s_cbranch_scc1 .LBB0_559
	v_pk_fma_f32 v[182:183], v[142:143], v[174:175], v[110:111] op_sel_hi:[1,0,1]
	v_pk_fma_f32 v[180:181], v[144:145], v[174:175], v[112:113] op_sel_hi:[1,0,1]
	v_mul_f32_e32 v0, 0xbfb8aa3b, v182
	v_exp_f32_e32 v0, v0
	v_pk_fma_f32 v[178:179], v[140:141], v[174:175], v[108:109] op_sel_hi:[1,0,1]
	v_pk_fma_f32 v[184:185], v[138:139], v[174:175], v[106:107] op_sel_hi:[1,0,1]
	v_mul_f32_e32 v178, 0xbfb8aa3b, v178
	v_add_f32_e32 v0, 1.0, v0
	v_exp_f32_e32 v178, v178
	v_lshlrev_b64 v[176:177], 12, v[158:159]
	s_add_i32 s30, s68, 0xfffff800
	v_rcp_f32_e32 v0, v0
	s_nop 0
	v_mul_f32_e32 v169, 0xbfb8aa3b, v184
	v_exp_f32_e32 v169, v169
	v_add_f32_e32 v178, 1.0, v178
	v_add_f32_e32 v169, 1.0, v169
	v_rcp_f32_e32 v169, v169
	s_nop 0
	v_mul_f32_e32 v171, 0xbfb8aa3b, v183
	v_exp_f32_e32 v171, v171
	s_nop 0
	v_add_f32_e32 v171, 1.0, v171
	v_rcp_f32_e32 v171, v171
	s_nop 0
	v_mul_f32_e32 v173, 0xbfb8aa3b, v185
	v_exp_f32_e32 v173, v173
	s_nop 0
	v_add_f32_e32 v173, 1.0, v173
	v_rcp_f32_e32 v173, v173
	s_nop 0
	v_mul_f32_e32 v175, 0xbfb8aa3b, v180
	v_exp_f32_e32 v175, v175
	s_nop 0
	v_add_f32_e32 v175, 1.0, v175
	v_rcp_f32_e32 v175, v175
	s_nop 0
	v_rcp_f32_e32 v182, v178
	s_nop 0
	v_mul_f32_e32 v178, 0xbfb8aa3b, v181
	v_exp_f32_e32 v178, v178
	s_nop 0
	v_add_f32_e32 v178, 1.0, v178
	v_rcp_f32_e32 v180, v178
	s_nop 0
	v_mul_f32_e32 v178, 0xbfb8aa3b, v179
	v_exp_f32_e32 v178, v178
	s_nop 0
	v_add_f32_e32 v178, 1.0, v178
	v_readlane_b32 s2, v255, 47
	v_readlane_b32 s3, v255, 48
	v_lshl_add_u64 v[176:177], s[2:3], 0, v[176:177]
	v_rcp_f32_e32 v181, v178
	s_nop 0
	v_lshl_add_u64 v[176:177], s[30:31], 1, v[176:177]
	s_lshl_b32 s30, s50, 1
	v_cvt_pk_bf16_f32 v178, v0, v171
	v_cvt_pk_bf16_f32 v179, v175, v180
	v_cvt_pk_bf16_f32 v180, v169, v173
	v_cvt_pk_bf16_f32 v181, v182, v181
	v_lshl_add_u64 v[176:177], v[176:177], 0, s[30:31]
	v_lshlrev_b32_e32 v0, 1, v167
	v_pk_fma_f32 v[182:183], v[134:135], v[174:175], v[94:95] op_sel_hi:[1,0,1]
	v_lshl_add_u64 v[176:177], v[176:177], 0, v[0:1]
	v_mul_f32_e32 v0, 0xbfb8aa3b, v182
	v_exp_f32_e32 v0, v0
	global_store_dwordx4 v[176:177], v[178:181], off
	v_pk_fma_f32 v[184:185], v[130:131], v[174:175], v[90:91] op_sel_hi:[1,0,1]
	v_add_f32_e32 v0, 1.0, v0
	v_div_scale_f32 v169, s[2:3], v0, v0, 1.0
	v_rcp_f32_e32 v171, v169
	v_pk_fma_f32 v[180:181], v[136:137], v[174:175], v[96:97] op_sel_hi:[1,0,1]
	v_pk_fma_f32 v[178:179], v[132:133], v[174:175], v[92:93] op_sel_hi:[1,0,1]
	v_fma_f32 v173, -v169, v171, 1.0
	v_fmac_f32_e32 v171, v173, v171
	v_div_scale_f32 v173, vcc, 1.0, v0, 1.0
	v_mul_f32_e32 v175, v173, v171
	v_fma_f32 v182, -v169, v175, v173
	v_fmac_f32_e32 v175, v182, v171
	v_fma_f32 v169, -v169, v175, v173
	v_div_fmas_f32 v169, v169, v171, v175
	v_div_fixup_f32 v0, v169, v0, 1.0
	v_mul_f32_e32 v169, 0xbfb8aa3b, v184
	v_exp_f32_e32 v169, v169
	v_mul_f32_e32 v178, 0xbfb8aa3b, v178
	v_exp_f32_e32 v178, v178
	v_add_f32_e32 v169, 1.0, v169
	v_add_f32_e32 v178, 1.0, v178
	v_rcp_f32_e32 v169, v169
	s_nop 0
	v_mul_f32_e32 v171, 0xbfb8aa3b, v183
	v_exp_f32_e32 v171, v171
	s_nop 0
	v_add_f32_e32 v171, 1.0, v171
	v_rcp_f32_e32 v171, v171
	s_nop 0
	v_mul_f32_e32 v173, 0xbfb8aa3b, v185
	v_exp_f32_e32 v173, v173
	s_nop 0
	v_add_f32_e32 v173, 1.0, v173
	v_rcp_f32_e32 v173, v173
	s_nop 0
	v_mul_f32_e32 v175, 0xbfb8aa3b, v180
	v_exp_f32_e32 v175, v175
	s_nop 0
	v_add_f32_e32 v175, 1.0, v175
	v_rcp_f32_e32 v175, v175
	s_nop 0
	v_rcp_f32_e32 v182, v178
	s_nop 0
	v_mul_f32_e32 v178, 0xbfb8aa3b, v181
	v_exp_f32_e32 v178, v178
	s_nop 0
	v_add_f32_e32 v178, 1.0, v178
	v_rcp_f32_e32 v180, v178
	s_nop 0
	v_mul_f32_e32 v178, 0xbfb8aa3b, v179
	v_exp_f32_e32 v178, v178
; __device__ __forceinline__ float sigmoidf_(float x) { return 1.0f / (1.0f + __builtin_amdgcn_exp2f(-1.4426950408889634f * x)); }
; #define EPIIN_PACK(w, a, b) do { (w).x = cvt_pk_bf16((a)[0], (a)[1]); (w).y = cvt_pk_bf16((a)[2], (a)[3]); (w).z = cvt_pk_bf16((b)[0], (b)[1]); (w).w = cvt_pk_bf16((b)[2], (b)[3]); } while (0)
;     __device__ __forceinline__ void operator()(const f32x4 (&acc_)[2][2][4][2], const Unit& u, int wr, int wc, int fr, int fq) const {
;     ...
; #pragma unroll
;             for (int ai = 0; ai < 2; ++ai)
; #pragma unroll
;                 for (int m = 0; m < 4; ++m) { const size_t row = rowb + ai * HALF + m * 16;
; #pragma unroll
;                     for (int bj = 0; bj < 2; ++bj) { f32x4 a = EPIIN_VAL(ai, bj, m, 0), b = EPIIN_VAL(ai, bj, m, 1);
; #pragma unroll
;                         for (int i = 0; i < 4; ++i) { a[i] = sigmoidf_(a[i]); b[i] = sigmoidf_(b[i]); }
;                         u32x4 w; EPIIN_PACK(w, a, b);
;                         *(u32x4*)(GATES + row * 2048 + (pn - 8) * 256 + bj * HALF + wc * 32 + fq * 8) = w; } }
	s_nop 0
	v_add_f32_e32 v178, 1.0, v178
	v_rcp_f32_e32 v181, v178
	s_nop 0
	v_cvt_pk_bf16_f32 v178, v0, v171
	v_cvt_pk_bf16_f32 v179, v175, v180
	v_cvt_pk_bf16_f32 v180, v169, v173
	v_cvt_pk_bf16_f32 v181, v182, v181
	v_pk_fma_f32 v[182:183], v[126:127], v[172:173], v[110:111] op_sel_hi:[1,0,1]
	global_store_dwordx4 v[176:177], v[178:181], off offset:256
	v_mul_f32_e32 v0, 0xbfb8aa3b, v182
	v_exp_f32_e32 v0, v0
	v_pk_fma_f32 v[180:181], v[128:129], v[172:173], v[112:113] op_sel_hi:[1,0,1]
	v_pk_fma_f32 v[178:179], v[124:125], v[172:173], v[108:109] op_sel_hi:[1,0,1]
	v_pk_fma_f32 v[184:185], v[122:123], v[172:173], v[106:107] op_sel_hi:[1,0,1]
	v_add_f32_e32 v0, 1.0, v0
	v_mul_f32_e32 v178, 0xbfb8aa3b, v178
	v_exp_f32_e32 v178, v178
	v_mul_f32_e32 v179, 0xbfb8aa3b, v179
	v_rcp_f32_e32 v0, v0
	s_nop 0
	v_mul_f32_e32 v169, 0xbfb8aa3b, v184
	v_exp_f32_e32 v169, v169
	v_add_f32_e32 v178, 1.0, v178
	v_exp_f32_e32 v179, v179
	v_add_f32_e32 v169, 1.0, v169
	v_add_f32_e32 v179, 1.0, v179
	v_rcp_f32_e32 v169, v169
	s_nop 0
	v_mul_f32_e32 v171, 0xbfb8aa3b, v183
	v_exp_f32_e32 v171, v171
	s_nop 0
	v_add_f32_e32 v171, 1.0, v171
	v_rcp_f32_e32 v171, v171
	s_nop 0
	v_mul_f32_e32 v173, 0xbfb8aa3b, v185
	v_exp_f32_e32 v173, v173
	s_nop 0
	v_add_f32_e32 v173, 1.0, v173
	v_rcp_f32_e32 v173, v173
	s_nop 0
	v_mul_f32_e32 v175, 0xbfb8aa3b, v180
	v_exp_f32_e32 v175, v175
	v_pk_fma_f32 v[186:187], v[114:115], v[172:173], v[90:91] op_sel_hi:[1,0,1]
	v_add_f32_e32 v175, 1.0, v175
	v_rcp_f32_e32 v175, v175
	s_nop 0
	v_rcp_f32_e32 v178, v178
	s_nop 0
	v_mul_f32_e32 v180, 0xbfb8aa3b, v181
	v_exp_f32_e32 v180, v180
	s_nop 0
	v_add_f32_e32 v180, 1.0, v180
	v_rcp_f32_e32 v181, v180
	s_nop 0
	s_mov_b64 s[2:3], 0x10000
	v_rcp_f32_e32 v179, v179
	s_nop 0
	v_cvt_pk_bf16_f32 v180, v0, v171
	v_cvt_pk_bf16_f32 v181, v175, v181
	v_cvt_pk_bf16_f32 v182, v169, v173
	v_cvt_pk_bf16_f32 v183, v178, v179
	v_lshl_add_u64 v[178:179], v[176:177], 0, s[2:3]
	s_mov_b32 s2, 0x10000
	v_add_co_u32_e32 v184, vcc, s2, v176
	s_nop 1
	v_addc_co_u32_e32 v185, vcc, 0, v177, vcc
	global_store_dwordx4 v[184:185], v[180:183], off
	v_pk_fma_f32 v[184:185], v[118:119], v[172:173], v[94:95] op_sel_hi:[1,0,1]
	s_nop 0
	v_mul_f32_e32 v0, 0xbfb8aa3b, v184
	v_exp_f32_e32 v0, v0
	v_pk_fma_f32 v[182:183], v[120:121], v[172:173], v[96:97] op_sel_hi:[1,0,1]
	v_pk_fma_f32 v[180:181], v[116:117], v[172:173], v[92:93] op_sel_hi:[1,0,1]
	v_add_f32_e32 v0, 1.0, v0
	v_mul_f32_e32 v180, 0xbfb8aa3b, v180
	v_exp_f32_e32 v180, v180
	v_rcp_f32_e32 v0, v0
	s_nop 0
	v_mul_f32_e32 v169, 0xbfb8aa3b, v186
	v_exp_f32_e32 v169, v169
	v_add_f32_e32 v180, 1.0, v180
	v_add_f32_e32 v169, 1.0, v169
	v_rcp_f32_e32 v169, v169
	s_nop 0
	v_mul_f32_e32 v171, 0xbfb8aa3b, v185
	v_exp_f32_e32 v171, v171
	s_nop 0
	v_add_f32_e32 v171, 1.0, v171
	v_rcp_f32_e32 v171, v171
	s_nop 0
	v_mul_f32_e32 v173, 0xbfb8aa3b, v187
	v_exp_f32_e32 v173, v173
	s_nop 0
	v_add_f32_e32 v173, 1.0, v173
	v_rcp_f32_e32 v173, v173
	s_nop 0
	v_mul_f32_e32 v175, 0xbfb8aa3b, v182
	v_exp_f32_e32 v175, v175
	s_nop 0
	v_add_f32_e32 v175, 1.0, v175
	v_rcp_f32_e32 v175, v175
	s_nop 0
	v_rcp_f32_e32 v184, v180
	s_nop 0
	v_mul_f32_e32 v180, 0xbfb8aa3b, v183
	v_exp_f32_e32 v180, v180
	s_nop 0
	v_add_f32_e32 v180, 1.0, v180
	v_rcp_f32_e32 v182, v180
	s_nop 0
	v_mul_f32_e32 v180, 0xbfb8aa3b, v181
	v_exp_f32_e32 v180, v180
	s_nop 0
	v_add_f32_e32 v180, 1.0, v180
	v_rcp_f32_e32 v183, v180
	s_nop 0
	v_cvt_pk_bf16_f32 v180, v0, v171
	v_cvt_pk_bf16_f32 v181, v175, v182
	v_cvt_pk_bf16_f32 v182, v169, v173
	v_cvt_pk_bf16_f32 v183, v184, v183
	global_store_dwordx4 v[178:179], v[180:183], off offset:256
	v_pk_fma_f32 v[178:179], v[100:101], v[170:171], v[108:109] op_sel_hi:[1,0,1]
	v_pk_fma_f32 v[184:185], v[98:99], v[170:171], v[106:107] op_sel_hi:[1,0,1]
	v_pk_fma_f32 v[182:183], v[102:103], v[170:171], v[110:111] op_sel_hi:[1,0,1]
	v_pk_fma_f32 v[180:181], v[104:105], v[170:171], v[112:113] op_sel_hi:[1,0,1]
	v_mul_f32_e32 v0, 0xbfb8aa3b, v182
	v_exp_f32_e32 v0, v0
	v_mul_f32_e32 v178, 0xbfb8aa3b, v178
	v_exp_f32_e32 v178, v178
	v_mul_f32_e32 v179, 0xbfb8aa3b, v179
	v_add_f32_e32 v0, 1.0, v0
	v_add_f32_e32 v178, 1.0, v178
	v_exp_f32_e32 v179, v179
	v_rcp_f32_e32 v0, v0
	s_nop 0
	v_mul_f32_e32 v169, 0xbfb8aa3b, v184
	v_exp_f32_e32 v169, v169
	v_add_f32_e32 v179, 1.0, v179
	v_add_f32_e32 v169, 1.0, v169
	v_rcp_f32_e32 v169, v169
	s_nop 0
	v_mul_f32_e32 v171, 0xbfb8aa3b, v183
	v_exp_f32_e32 v171, v171
	s_nop 0
	v_add_f32_e32 v171, 1.0, v171
	v_rcp_f32_e32 v171, v171
	s_nop 0
	v_mul_f32_e32 v173, 0xbfb8aa3b, v185
	v_exp_f32_e32 v173, v173
	v_pk_fma_f32 v[186:187], v[82:83], v[170:171], v[90:91] op_sel_hi:[1,0,1]
	v_add_f32_e32 v173, 1.0, v173
	v_rcp_f32_e32 v173, v173
	s_nop 0
	v_mul_f32_e32 v175, 0xbfb8aa3b, v180
	v_exp_f32_e32 v175, v175
	s_nop 0
	v_add_f32_e32 v175, 1.0, v175
	v_rcp_f32_e32 v175, v175
	s_nop 0
	v_rcp_f32_e32 v178, v178
	s_nop 0
	v_mul_f32_e32 v180, 0xbfb8aa3b, v181
	v_exp_f32_e32 v180, v180
	s_nop 0
	v_add_f32_e32 v180, 1.0, v180
	v_rcp_f32_e32 v181, v180
	s_nop 0
	s_mov_b64 s[2:3], 0x20000
	v_rcp_f32_e32 v179, v179
	s_nop 0
	v_cvt_pk_bf16_f32 v180, v0, v171
	v_cvt_pk_bf16_f32 v181, v175, v181
	v_cvt_pk_bf16_f32 v182, v169, v173
	v_cvt_pk_bf16_f32 v183, v178, v179
	v_lshl_add_u64 v[178:179], v[176:177], 0, s[2:3]
	s_mov_b32 s2, 0x20000
	v_add_co_u32_e32 v184, vcc, s2, v176
	s_nop 1
	v_addc_co_u32_e32 v185, vcc, 0, v177, vcc
	global_store_dwordx4 v[184:185], v[180:183], off
	v_pk_fma_f32 v[184:185], v[86:87], v[170:171], v[94:95] op_sel_hi:[1,0,1]
	s_nop 0
	v_mul_f32_e32 v0, 0xbfb8aa3b, v184
	v_exp_f32_e32 v0, v0
	v_pk_fma_f32 v[182:183], v[88:89], v[170:171], v[96:97] op_sel_hi:[1,0,1]
; __device__ __forceinline__ float sigmoidf_(float x) { return 1.0f / (1.0f + __builtin_amdgcn_exp2f(-1.4426950408889634f * x)); }
; #define EPIIN_PACK(w, a, b) do { (w).x = cvt_pk_bf16((a)[0], (a)[1]); (w).y = cvt_pk_bf16((a)[2], (a)[3]); (w).z = cvt_pk_bf16((b)[0], (b)[1]); (w).w = cvt_pk_bf16((b)[2], (b)[3]); } while (0)
;     __device__ __forceinline__ void operator()(const f32x4 (&acc_)[2][2][4][2], const Unit& u, int wr, int wc, int fr, int fq) const {
;     ...
; #pragma unroll
;             for (int ai = 0; ai < 2; ++ai)
; #pragma unroll
;                 for (int m = 0; m < 4; ++m) { const size_t row = rowb + ai * HALF + m * 16;
; #pragma unroll
;                     for (int bj = 0; bj < 2; ++bj) { f32x4 a = EPIIN_VAL(ai, bj, m, 0), b = EPIIN_VAL(ai, bj, m, 1);
; #pragma unroll
;                         for (int i = 0; i < 4; ++i) { a[i] = sigmoidf_(a[i]); b[i] = sigmoidf_(b[i]); }
;                         u32x4 w; EPIIN_PACK(w, a, b);
;                         *(u32x4*)(GATES + row * 2048 + (pn - 8) * 256 + bj * HALF + wc * 32 + fq * 8) = w; } }
	v_pk_fma_f32 v[180:181], v[84:85], v[170:171], v[92:93] op_sel_hi:[1,0,1]
	v_add_f32_e32 v0, 1.0, v0
	v_mul_f32_e32 v180, 0xbfb8aa3b, v180
	v_exp_f32_e32 v180, v180
	v_rcp_f32_e32 v0, v0
	s_nop 0
	v_mul_f32_e32 v169, 0xbfb8aa3b, v186
	v_exp_f32_e32 v169, v169
	v_add_f32_e32 v180, 1.0, v180
	v_add_f32_e32 v169, 1.0, v169
	v_rcp_f32_e32 v169, v169
	s_nop 0
	v_mul_f32_e32 v171, 0xbfb8aa3b, v185
	v_exp_f32_e32 v171, v171
	s_nop 0
	v_add_f32_e32 v171, 1.0, v171
	v_rcp_f32_e32 v171, v171
	s_nop 0
	v_mul_f32_e32 v173, 0xbfb8aa3b, v187
	v_exp_f32_e32 v173, v173
	s_nop 0
	v_add_f32_e32 v173, 1.0, v173
	v_rcp_f32_e32 v173, v173
	s_nop 0
	v_mul_f32_e32 v175, 0xbfb8aa3b, v182
	v_exp_f32_e32 v175, v175
	s_nop 0
	v_add_f32_e32 v175, 1.0, v175
	v_rcp_f32_e32 v175, v175
	s_nop 0
	v_rcp_f32_e32 v184, v180
	s_nop 0
	v_mul_f32_e32 v180, 0xbfb8aa3b, v183
	v_exp_f32_e32 v180, v180
	s_nop 0
	v_add_f32_e32 v180, 1.0, v180
	v_rcp_f32_e32 v182, v180
	s_nop 0
	v_mul_f32_e32 v180, 0xbfb8aa3b, v181
	v_exp_f32_e32 v180, v180
	s_nop 0
	v_add_f32_e32 v180, 1.0, v180
	v_rcp_f32_e32 v183, v180
	s_nop 0
	v_cvt_pk_bf16_f32 v180, v0, v171
	v_cvt_pk_bf16_f32 v181, v175, v182
	v_cvt_pk_bf16_f32 v182, v169, v173
	v_cvt_pk_bf16_f32 v183, v184, v183
	global_store_dwordx4 v[178:179], v[180:183], off offset:256
	v_pk_fma_f32 v[178:179], v[76:77], v[168:169], v[108:109] op_sel_hi:[1,0,1]
	v_pk_fma_f32 v[184:185], v[74:75], v[168:169], v[106:107] op_sel_hi:[1,0,1]
	v_pk_fma_f32 v[182:183], v[78:79], v[168:169], v[110:111] op_sel_hi:[1,0,1]
	v_pk_fma_f32 v[180:181], v[80:81], v[168:169], v[112:113] op_sel_hi:[1,0,1]
	v_mul_f32_e32 v0, 0xbfb8aa3b, v182
	v_exp_f32_e32 v0, v0
	v_mul_f32_e32 v178, 0xbfb8aa3b, v178
	v_exp_f32_e32 v178, v178
	v_mul_f32_e32 v179, 0xbfb8aa3b, v179
	v_add_f32_e32 v0, 1.0, v0
	v_add_f32_e32 v178, 1.0, v178
	v_exp_f32_e32 v179, v179
	v_rcp_f32_e32 v0, v0
	s_nop 0
	v_mul_f32_e32 v169, 0xbfb8aa3b, v184
	v_exp_f32_e32 v169, v169
	v_add_f32_e32 v179, 1.0, v179
	v_add_f32_e32 v169, 1.0, v169
	v_rcp_f32_e32 v169, v169
	s_nop 0
	v_mul_f32_e32 v171, 0xbfb8aa3b, v183
	v_exp_f32_e32 v171, v171
	v_pk_fma_f32 v[186:187], v[66:67], v[168:169], v[90:91] op_sel_hi:[1,0,1]
	v_add_f32_e32 v171, 1.0, v171
	v_rcp_f32_e32 v171, v171
	s_nop 0
	v_mul_f32_e32 v173, 0xbfb8aa3b, v185
	v_exp_f32_e32 v173, v173
	s_nop 0
	v_add_f32_e32 v173, 1.0, v173
	v_rcp_f32_e32 v173, v173
	s_nop 0
	v_mul_f32_e32 v175, 0xbfb8aa3b, v180
	v_exp_f32_e32 v175, v175
	s_nop 0
	v_add_f32_e32 v175, 1.0, v175
	v_rcp_f32_e32 v175, v175
	s_nop 0
	v_rcp_f32_e32 v178, v178
	s_nop 0
	v_mul_f32_e32 v180, 0xbfb8aa3b, v181
	v_exp_f32_e32 v180, v180
	s_nop 0
	v_add_f32_e32 v180, 1.0, v180
	v_rcp_f32_e32 v181, v180
	s_nop 0
	s_mov_b64 s[2:3], 0x30000
	v_rcp_f32_e32 v179, v179
	s_nop 0
	v_cvt_pk_bf16_f32 v180, v0, v171
	v_cvt_pk_bf16_f32 v181, v175, v181
	v_cvt_pk_bf16_f32 v182, v169, v173
	v_cvt_pk_bf16_f32 v183, v178, v179
	v_lshl_add_u64 v[178:179], v[176:177], 0, s[2:3]
	s_mov_b32 s2, 0x30000
	v_add_co_u32_e32 v184, vcc, s2, v176
	s_nop 1
	v_addc_co_u32_e32 v185, vcc, 0, v177, vcc
	global_store_dwordx4 v[184:185], v[180:183], off
	v_pk_fma_f32 v[184:185], v[70:71], v[168:169], v[94:95] op_sel_hi:[1,0,1]
	s_nop 0
	v_mul_f32_e32 v0, 0xbfb8aa3b, v184
	v_exp_f32_e32 v0, v0
	v_pk_fma_f32 v[182:183], v[72:73], v[168:169], v[96:97] op_sel_hi:[1,0,1]
	v_pk_fma_f32 v[180:181], v[68:69], v[168:169], v[92:93] op_sel_hi:[1,0,1]
	v_add_f32_e32 v0, 1.0, v0
	v_mul_f32_e32 v180, 0xbfb8aa3b, v180
	v_exp_f32_e32 v180, v180
	v_rcp_f32_e32 v0, v0
	s_nop 0
	v_mul_f32_e32 v169, 0xbfb8aa3b, v186
	v_exp_f32_e32 v169, v169
	v_add_f32_e32 v180, 1.0, v180
	v_add_f32_e32 v169, 1.0, v169
	v_rcp_f32_e32 v169, v169
	s_nop 0
	v_mul_f32_e32 v171, 0xbfb8aa3b, v185
	v_exp_f32_e32 v171, v171
	s_nop 0
	v_add_f32_e32 v171, 1.0, v171
	v_rcp_f32_e32 v171, v171
	s_nop 0
	v_mul_f32_e32 v173, 0xbfb8aa3b, v187
	v_exp_f32_e32 v173, v173
	s_nop 0
	v_add_f32_e32 v173, 1.0, v173
	v_rcp_f32_e32 v173, v173
	s_nop 0
	v_mul_f32_e32 v175, 0xbfb8aa3b, v182
	v_exp_f32_e32 v175, v175
	s_nop 0
	v_add_f32_e32 v175, 1.0, v175
	v_rcp_f32_e32 v175, v175
	s_nop 0
	v_rcp_f32_e32 v184, v180
	s_nop 0
	v_mul_f32_e32 v180, 0xbfb8aa3b, v183
	v_exp_f32_e32 v180, v180
	s_nop 0
	v_add_f32_e32 v180, 1.0, v180
	v_rcp_f32_e32 v182, v180
	s_nop 0
	v_mul_f32_e32 v180, 0xbfb8aa3b, v181
	v_exp_f32_e32 v180, v180
	s_nop 0
	v_add_f32_e32 v180, 1.0, v180
	v_rcp_f32_e32 v183, v180
	s_nop 0
	v_cvt_pk_bf16_f32 v180, v0, v171
	v_cvt_pk_bf16_f32 v181, v175, v182
	v_cvt_pk_bf16_f32 v182, v169, v173
	v_cvt_pk_bf16_f32 v183, v184, v183
	global_store_dwordx4 v[178:179], v[180:183], off offset:256
	v_pk_fma_f32 v[184:185], v[58:59], v[166:167], v[106:107] op_sel_hi:[1,0,1]
	v_pk_fma_f32 v[178:179], v[60:61], v[166:167], v[108:109] op_sel_hi:[1,0,1]
	v_pk_fma_f32 v[182:183], v[62:63], v[166:167], v[110:111] op_sel_hi:[1,0,1]
	v_pk_fma_f32 v[180:181], v[64:65], v[166:167], v[112:113] op_sel_hi:[1,0,1]
	v_mul_f32_e32 v0, 0xbfb8aa3b, v182
	v_exp_f32_e32 v0, v0
	v_mul_f32_e32 v178, 0xbfb8aa3b, v178
	v_exp_f32_e32 v178, v178
	v_mul_f32_e32 v179, 0xbfb8aa3b, v179
	v_add_f32_e32 v0, 1.0, v0
	v_add_f32_e32 v178, 1.0, v178
	v_exp_f32_e32 v179, v179
	v_pk_fma_f32 v[186:187], v[50:51], v[166:167], v[90:91] op_sel_hi:[1,0,1]
	v_rcp_f32_e32 v0, v0
	s_nop 0
	v_mul_f32_e32 v169, 0xbfb8aa3b, v184
	v_exp_f32_e32 v169, v169
	v_add_f32_e32 v179, 1.0, v179
	v_add_f32_e32 v169, 1.0, v169
	v_rcp_f32_e32 v169, v169
	s_nop 0
	v_mul_f32_e32 v171, 0xbfb8aa3b, v183
	v_exp_f32_e32 v171, v171
	s_nop 0
	v_add_f32_e32 v171, 1.0, v171
	v_rcp_f32_e32 v171, v171
	s_nop 0
	v_mul_f32_e32 v173, 0xbfb8aa3b, v185
	v_exp_f32_e32 v173, v173
; __device__ __forceinline__ float sigmoidf_(float x) { return 1.0f / (1.0f + __builtin_amdgcn_exp2f(-1.4426950408889634f * x)); }
; #define EPIIN_PACK(w, a, b) do { (w).x = cvt_pk_bf16((a)[0], (a)[1]); (w).y = cvt_pk_bf16((a)[2], (a)[3]); (w).z = cvt_pk_bf16((b)[0], (b)[1]); (w).w = cvt_pk_bf16((b)[2], (b)[3]); } while (0)
;     __device__ __forceinline__ void operator()(const f32x4 (&acc_)[2][2][4][2], const Unit& u, int wr, int wc, int fr, int fq) const {
;     ...
; #pragma unroll
;             for (int ai = 0; ai < 2; ++ai)
; #pragma unroll
;                 for (int m = 0; m < 4; ++m) { const size_t row = rowb + ai * HALF + m * 16;
; #pragma unroll
;                     for (int bj = 0; bj < 2; ++bj) { f32x4 a = EPIIN_VAL(ai, bj, m, 0), b = EPIIN_VAL(ai, bj, m, 1);
; #pragma unroll
;                         for (int i = 0; i < 4; ++i) { a[i] = sigmoidf_(a[i]); b[i] = sigmoidf_(b[i]); }
;                         u32x4 w; EPIIN_PACK(w, a, b);
;                         *(u32x4*)(GATES + row * 2048 + (pn - 8) * 256 + bj * HALF + wc * 32 + fq * 8) = w; } }
	s_nop 0
	v_add_f32_e32 v173, 1.0, v173
	v_rcp_f32_e32 v173, v173
	s_nop 0
	v_mul_f32_e32 v175, 0xbfb8aa3b, v180
	v_exp_f32_e32 v175, v175
	s_nop 0
	v_add_f32_e32 v175, 1.0, v175
	v_rcp_f32_e32 v175, v175
	s_nop 0
	v_rcp_f32_e32 v178, v178
	s_nop 0
	v_mul_f32_e32 v180, 0xbfb8aa3b, v181
	v_exp_f32_e32 v180, v180
	s_nop 0
	v_add_f32_e32 v180, 1.0, v180
	v_rcp_f32_e32 v181, v180
	s_nop 0
	s_mov_b64 s[2:3], 0x80000
	v_rcp_f32_e32 v179, v179
	s_nop 0
	v_cvt_pk_bf16_f32 v180, v0, v171
	v_cvt_pk_bf16_f32 v181, v175, v181
	v_cvt_pk_bf16_f32 v182, v169, v173
	v_cvt_pk_bf16_f32 v183, v178, v179
	v_lshl_add_u64 v[178:179], v[176:177], 0, s[2:3]
	s_mov_b32 s2, 0x80000
	v_add_co_u32_e32 v184, vcc, s2, v176
	s_nop 1
	v_addc_co_u32_e32 v185, vcc, 0, v177, vcc
	global_store_dwordx4 v[184:185], v[180:183], off
	v_pk_fma_f32 v[184:185], v[54:55], v[166:167], v[94:95] op_sel_hi:[1,0,1]
	s_nop 0
	v_mul_f32_e32 v0, 0xbfb8aa3b, v184
	v_exp_f32_e32 v0, v0
	v_pk_fma_f32 v[182:183], v[56:57], v[166:167], v[96:97] op_sel_hi:[1,0,1]
	v_pk_fma_f32 v[180:181], v[52:53], v[166:167], v[92:93] op_sel_hi:[1,0,1]
	v_add_f32_e32 v0, 1.0, v0
	v_mul_f32_e32 v180, 0xbfb8aa3b, v180
	v_exp_f32_e32 v180, v180
	v_rcp_f32_e32 v0, v0
	s_nop 0
	v_mul_f32_e32 v169, 0xbfb8aa3b, v186
	v_exp_f32_e32 v169, v169
	v_add_f32_e32 v180, 1.0, v180
	v_add_f32_e32 v169, 1.0, v169
	v_rcp_f32_e32 v169, v169
	s_nop 0
	v_mul_f32_e32 v171, 0xbfb8aa3b, v185
	v_exp_f32_e32 v171, v171
	s_nop 0
	v_add_f32_e32 v171, 1.0, v171
	v_rcp_f32_e32 v171, v171
	s_nop 0
	v_mul_f32_e32 v173, 0xbfb8aa3b, v187
	v_exp_f32_e32 v173, v173
	s_nop 0
	v_add_f32_e32 v173, 1.0, v173
	v_rcp_f32_e32 v173, v173
	s_nop 0
	v_mul_f32_e32 v175, 0xbfb8aa3b, v182
	v_exp_f32_e32 v175, v175
	s_nop 0
	v_add_f32_e32 v175, 1.0, v175
	v_rcp_f32_e32 v175, v175
	s_nop 0
	v_rcp_f32_e32 v184, v180
	s_nop 0
	v_mul_f32_e32 v180, 0xbfb8aa3b, v183
	v_exp_f32_e32 v180, v180
	s_nop 0
	v_add_f32_e32 v180, 1.0, v180
	v_rcp_f32_e32 v182, v180
	s_nop 0
	v_mul_f32_e32 v180, 0xbfb8aa3b, v181
	v_exp_f32_e32 v180, v180
	s_nop 0
	v_add_f32_e32 v180, 1.0, v180
	v_rcp_f32_e32 v183, v180
	s_nop 0
	v_cvt_pk_bf16_f32 v180, v0, v171
	v_cvt_pk_bf16_f32 v181, v175, v182
	v_cvt_pk_bf16_f32 v182, v169, v173
	v_cvt_pk_bf16_f32 v183, v184, v183
	global_store_dwordx4 v[178:179], v[180:183], off offset:256
	v_pk_fma_f32 v[184:185], v[42:43], v[164:165], v[106:107] op_sel_hi:[1,0,1]
	v_pk_fma_f32 v[178:179], v[44:45], v[164:165], v[108:109] op_sel_hi:[1,0,1]
	v_pk_fma_f32 v[182:183], v[46:47], v[164:165], v[110:111] op_sel_hi:[1,0,1]
	v_pk_fma_f32 v[180:181], v[48:49], v[164:165], v[112:113] op_sel_hi:[1,0,1]
	v_mul_f32_e32 v0, 0xbfb8aa3b, v182
	v_exp_f32_e32 v0, v0
	v_mul_f32_e32 v178, 0xbfb8aa3b, v178
	v_exp_f32_e32 v178, v178
	v_mul_f32_e32 v179, 0xbfb8aa3b, v179
	v_add_f32_e32 v0, 1.0, v0
	v_add_f32_e32 v178, 1.0, v178
	v_exp_f32_e32 v179, v179
	v_pk_fma_f32 v[186:187], v[34:35], v[164:165], v[90:91] op_sel_hi:[1,0,1]
	v_rcp_f32_e32 v0, v0
	s_nop 0
	v_mul_f32_e32 v169, 0xbfb8aa3b, v184
	v_exp_f32_e32 v169, v169
	v_add_f32_e32 v179, 1.0, v179
	v_add_f32_e32 v169, 1.0, v169
	v_rcp_f32_e32 v169, v169
	s_nop 0
	v_mul_f32_e32 v171, 0xbfb8aa3b, v183
	v_exp_f32_e32 v171, v171
	s_nop 0
	v_add_f32_e32 v171, 1.0, v171
	v_rcp_f32_e32 v171, v171
	s_nop 0
	v_mul_f32_e32 v173, 0xbfb8aa3b, v185
	v_exp_f32_e32 v173, v173
	s_nop 0
	v_add_f32_e32 v173, 1.0, v173
	v_rcp_f32_e32 v173, v173
	s_nop 0
	v_mul_f32_e32 v175, 0xbfb8aa3b, v180
	v_exp_f32_e32 v175, v175
	s_nop 0
	v_add_f32_e32 v175, 1.0, v175
	v_rcp_f32_e32 v175, v175
	s_nop 0
	v_rcp_f32_e32 v178, v178
	s_nop 0
	v_mul_f32_e32 v180, 0xbfb8aa3b, v181
	v_exp_f32_e32 v180, v180
	s_nop 0
	v_add_f32_e32 v180, 1.0, v180
	v_rcp_f32_e32 v181, v180
	s_nop 0
	s_mov_b64 s[2:3], 0x90000
	v_rcp_f32_e32 v179, v179
	s_nop 0
	v_cvt_pk_bf16_f32 v180, v0, v171
	v_cvt_pk_bf16_f32 v181, v175, v181
	v_cvt_pk_bf16_f32 v182, v169, v173
	v_cvt_pk_bf16_f32 v183, v178, v179
	v_lshl_add_u64 v[178:179], v[176:177], 0, s[2:3]
	s_mov_b32 s2, 0x90000
	v_add_co_u32_e32 v184, vcc, s2, v176
	s_nop 1
	v_addc_co_u32_e32 v185, vcc, 0, v177, vcc
	global_store_dwordx4 v[184:185], v[180:183], off
	v_pk_fma_f32 v[184:185], v[38:39], v[164:165], v[94:95] op_sel_hi:[1,0,1]
	s_nop 0
	v_mul_f32_e32 v0, 0xbfb8aa3b, v184
	v_exp_f32_e32 v0, v0
	v_pk_fma_f32 v[182:183], v[40:41], v[164:165], v[96:97] op_sel_hi:[1,0,1]
	v_pk_fma_f32 v[180:181], v[36:37], v[164:165], v[92:93] op_sel_hi:[1,0,1]
	v_add_f32_e32 v0, 1.0, v0
	v_mul_f32_e32 v180, 0xbfb8aa3b, v180
	v_exp_f32_e32 v180, v180
	v_rcp_f32_e32 v0, v0
	s_nop 0
	v_mul_f32_e32 v169, 0xbfb8aa3b, v186
	v_exp_f32_e32 v169, v169
	v_add_f32_e32 v180, 1.0, v180
	v_add_f32_e32 v169, 1.0, v169
	v_rcp_f32_e32 v169, v169
	s_nop 0
	v_mul_f32_e32 v171, 0xbfb8aa3b, v185
	v_exp_f32_e32 v171, v171
	s_nop 0
	v_add_f32_e32 v171, 1.0, v171
	v_rcp_f32_e32 v171, v171
	s_nop 0
	v_mul_f32_e32 v173, 0xbfb8aa3b, v187
	v_exp_f32_e32 v173, v173
	s_nop 0
	v_add_f32_e32 v173, 1.0, v173
	v_rcp_f32_e32 v173, v173
	s_nop 0
	v_mul_f32_e32 v175, 0xbfb8aa3b, v182
	v_exp_f32_e32 v175, v175
	s_nop 0
	v_add_f32_e32 v175, 1.0, v175
	v_rcp_f32_e32 v175, v175
	s_nop 0
	v_rcp_f32_e32 v184, v180
	s_nop 0
	v_mul_f32_e32 v180, 0xbfb8aa3b, v183
	v_exp_f32_e32 v180, v180
	s_nop 0
	v_add_f32_e32 v180, 1.0, v180
	v_rcp_f32_e32 v182, v180
	s_nop 0
	v_mul_f32_e32 v180, 0xbfb8aa3b, v181
	v_exp_f32_e32 v180, v180
	s_nop 0
	v_add_f32_e32 v180, 1.0, v180
	v_rcp_f32_e32 v183, v180
	s_nop 0
	v_cvt_pk_bf16_f32 v180, v0, v171
	v_cvt_pk_bf16_f32 v181, v175, v182
	v_cvt_pk_bf16_f32 v182, v169, v173
	v_cvt_pk_bf16_f32 v183, v184, v183
	global_store_dwordx4 v[178:179], v[180:183], off offset:256
; __device__ __forceinline__ float sigmoidf_(float x) { return 1.0f / (1.0f + __builtin_amdgcn_exp2f(-1.4426950408889634f * x)); }
; #define EPIIN_PACK(w, a, b) do { (w).x = cvt_pk_bf16((a)[0], (a)[1]); (w).y = cvt_pk_bf16((a)[2], (a)[3]); (w).z = cvt_pk_bf16((b)[0], (b)[1]); (w).w = cvt_pk_bf16((b)[2], (b)[3]); } while (0)
;     __device__ __forceinline__ void operator()(const f32x4 (&acc_)[2][2][4][2], const Unit& u, int wr, int wc, int fr, int fq) const {
;     ...
; #pragma unroll
;             for (int ai = 0; ai < 2; ++ai)
; #pragma unroll
;                 for (int m = 0; m < 4; ++m) { const size_t row = rowb + ai * HALF + m * 16;
; #pragma unroll
;                     for (int bj = 0; bj < 2; ++bj) { f32x4 a = EPIIN_VAL(ai, bj, m, 0), b = EPIIN_VAL(ai, bj, m, 1);
; #pragma unroll
;                         for (int i = 0; i < 4; ++i) { a[i] = sigmoidf_(a[i]); b[i] = sigmoidf_(b[i]); }
;                         u32x4 w; EPIIN_PACK(w, a, b);
;                         *(u32x4*)(GATES + row * 2048 + (pn - 8) * 256 + bj * HALF + wc * 32 + fq * 8) = w; } }
	v_pk_fma_f32 v[184:185], v[26:27], v[162:163], v[106:107] op_sel_hi:[1,0,1]
	v_pk_fma_f32 v[178:179], v[28:29], v[162:163], v[108:109] op_sel_hi:[1,0,1]
	v_pk_fma_f32 v[182:183], v[30:31], v[162:163], v[110:111] op_sel_hi:[1,0,1]
	v_pk_fma_f32 v[180:181], v[32:33], v[162:163], v[112:113] op_sel_hi:[1,0,1]
	v_mul_f32_e32 v0, 0xbfb8aa3b, v182
	v_exp_f32_e32 v0, v0
	v_mul_f32_e32 v178, 0xbfb8aa3b, v178
	v_exp_f32_e32 v178, v178
	v_mul_f32_e32 v179, 0xbfb8aa3b, v179
	v_add_f32_e32 v0, 1.0, v0
	v_add_f32_e32 v178, 1.0, v178
	v_exp_f32_e32 v179, v179
	v_pk_fma_f32 v[186:187], v[18:19], v[162:163], v[90:91] op_sel_hi:[1,0,1]
	v_rcp_f32_e32 v0, v0
	s_nop 0
	v_mul_f32_e32 v169, 0xbfb8aa3b, v184
	v_exp_f32_e32 v169, v169
	v_add_f32_e32 v179, 1.0, v179
	v_add_f32_e32 v169, 1.0, v169
	v_rcp_f32_e32 v169, v169
	s_nop 0
	v_mul_f32_e32 v171, 0xbfb8aa3b, v183
	v_exp_f32_e32 v171, v171
	s_nop 0
	v_add_f32_e32 v171, 1.0, v171
	v_rcp_f32_e32 v171, v171
	s_nop 0
	v_mul_f32_e32 v173, 0xbfb8aa3b, v185
	v_exp_f32_e32 v173, v173
	s_nop 0
	v_add_f32_e32 v173, 1.0, v173
	v_rcp_f32_e32 v173, v173
	s_nop 0
	v_mul_f32_e32 v175, 0xbfb8aa3b, v180
	v_exp_f32_e32 v175, v175
	s_nop 0
	v_add_f32_e32 v175, 1.0, v175
	v_rcp_f32_e32 v175, v175
	s_nop 0
	v_rcp_f32_e32 v178, v178
	s_nop 0
	v_mul_f32_e32 v180, 0xbfb8aa3b, v181
	v_exp_f32_e32 v180, v180
	s_nop 0
	v_add_f32_e32 v180, 1.0, v180
	v_rcp_f32_e32 v181, v180
	s_nop 0
	s_mov_b64 s[2:3], 0xa0000
	v_rcp_f32_e32 v179, v179
	s_nop 0
	v_cvt_pk_bf16_f32 v180, v0, v171
	v_cvt_pk_bf16_f32 v181, v175, v181
	v_cvt_pk_bf16_f32 v182, v169, v173
	v_cvt_pk_bf16_f32 v183, v178, v179
	v_lshl_add_u64 v[178:179], v[176:177], 0, s[2:3]
	s_mov_b32 s2, 0xa0000
	v_add_co_u32_e32 v184, vcc, s2, v176
	s_nop 1
	v_addc_co_u32_e32 v185, vcc, 0, v177, vcc
	global_store_dwordx4 v[184:185], v[180:183], off
	v_pk_fma_f32 v[184:185], v[22:23], v[162:163], v[94:95] op_sel_hi:[1,0,1]
	s_nop 0
	v_mul_f32_e32 v0, 0xbfb8aa3b, v184
	v_exp_f32_e32 v0, v0
	v_pk_fma_f32 v[182:183], v[24:25], v[162:163], v[96:97] op_sel_hi:[1,0,1]
	v_pk_fma_f32 v[180:181], v[20:21], v[162:163], v[92:93] op_sel_hi:[1,0,1]
	v_add_f32_e32 v0, 1.0, v0
	v_mul_f32_e32 v180, 0xbfb8aa3b, v180
	v_exp_f32_e32 v180, v180
	v_rcp_f32_e32 v0, v0
	s_nop 0
	v_mul_f32_e32 v169, 0xbfb8aa3b, v186
	v_exp_f32_e32 v169, v169
	v_add_f32_e32 v180, 1.0, v180
	v_add_f32_e32 v169, 1.0, v169
	v_rcp_f32_e32 v169, v169
	s_nop 0
	v_mul_f32_e32 v171, 0xbfb8aa3b, v185
	v_exp_f32_e32 v171, v171
	s_nop 0
	v_add_f32_e32 v171, 1.0, v171
	v_rcp_f32_e32 v171, v171
	s_nop 0
	v_mul_f32_e32 v173, 0xbfb8aa3b, v187
	v_exp_f32_e32 v173, v173
	s_nop 0
	v_add_f32_e32 v173, 1.0, v173
	v_rcp_f32_e32 v173, v173
	s_nop 0
	v_mul_f32_e32 v175, 0xbfb8aa3b, v182
	v_exp_f32_e32 v175, v175
	s_nop 0
	v_add_f32_e32 v175, 1.0, v175
	v_rcp_f32_e32 v175, v175
	s_nop 0
	v_rcp_f32_e32 v184, v180
	s_nop 0
	v_mul_f32_e32 v180, 0xbfb8aa3b, v183
	v_exp_f32_e32 v180, v180
	s_nop 0
	v_add_f32_e32 v180, 1.0, v180
	v_rcp_f32_e32 v182, v180
	s_nop 0
	v_mul_f32_e32 v180, 0xbfb8aa3b, v181
	v_exp_f32_e32 v180, v180
	s_nop 0
	v_add_f32_e32 v180, 1.0, v180
	v_rcp_f32_e32 v183, v180
	s_nop 0
	v_cvt_pk_bf16_f32 v180, v0, v171
	v_cvt_pk_bf16_f32 v181, v175, v182
	v_cvt_pk_bf16_f32 v182, v169, v173
	v_cvt_pk_bf16_f32 v183, v184, v183
	global_store_dwordx4 v[178:179], v[180:183], off offset:256
	v_pk_fma_f32 v[184:185], v[10:11], v[160:161], v[106:107] op_sel_hi:[1,0,1]
	v_pk_fma_f32 v[178:179], v[12:13], v[160:161], v[108:109] op_sel_hi:[1,0,1]
	v_pk_fma_f32 v[182:183], v[14:15], v[160:161], v[110:111] op_sel_hi:[1,0,1]
	v_pk_fma_f32 v[180:181], v[16:17], v[160:161], v[112:113] op_sel_hi:[1,0,1]
	v_mul_f32_e32 v0, 0xbfb8aa3b, v182
	v_exp_f32_e32 v0, v0
	v_mul_f32_e32 v178, 0xbfb8aa3b, v178
	v_exp_f32_e32 v178, v178
	v_mul_f32_e32 v179, 0xbfb8aa3b, v179
	v_add_f32_e32 v0, 1.0, v0
	v_add_f32_e32 v178, 1.0, v178
	v_exp_f32_e32 v179, v179
	v_rcp_f32_e32 v0, v0
	s_nop 0
	v_mul_f32_e32 v169, 0xbfb8aa3b, v184
	v_exp_f32_e32 v169, v169
	v_add_f32_e32 v179, 1.0, v179
	v_add_f32_e32 v169, 1.0, v169
	v_rcp_f32_e32 v169, v169
	s_nop 0
	v_mul_f32_e32 v171, 0xbfb8aa3b, v183
	v_exp_f32_e32 v171, v171
	s_nop 0
	v_add_f32_e32 v171, 1.0, v171
	v_rcp_f32_e32 v171, v171
	s_nop 0
	v_mul_f32_e32 v173, 0xbfb8aa3b, v185
	v_exp_f32_e32 v173, v173
	s_nop 0
	v_add_f32_e32 v173, 1.0, v173
	v_rcp_f32_e32 v173, v173
	s_nop 0
	v_mul_f32_e32 v175, 0xbfb8aa3b, v180
	v_exp_f32_e32 v175, v175
	s_nop 0
	v_add_f32_e32 v175, 1.0, v175
	v_rcp_f32_e32 v175, v175
	s_nop 0
	v_rcp_f32_e32 v178, v178
	s_nop 0
	v_mul_f32_e32 v180, 0xbfb8aa3b, v181
	v_exp_f32_e32 v180, v180
	s_nop 0
	v_add_f32_e32 v180, 1.0, v180
	v_rcp_f32_e32 v181, v180
	s_nop 0
	s_mov_b64 s[2:3], 0xb0000
	v_rcp_f32_e32 v179, v179
	s_nop 0
	v_cvt_pk_bf16_f32 v180, v0, v171
	v_cvt_pk_bf16_f32 v181, v175, v181
	v_cvt_pk_bf16_f32 v182, v169, v173
	v_cvt_pk_bf16_f32 v183, v178, v179
	v_lshl_add_u64 v[178:179], v[176:177], 0, s[2:3]
	s_mov_b32 s2, 0xb0000
	v_add_co_u32_e32 v176, vcc, s2, v176
	v_pk_fma_f32 v[184:185], v[2:3], v[160:161], v[90:91] op_sel_hi:[1,0,1]
	s_nop 0
	v_addc_co_u32_e32 v177, vcc, 0, v177, vcc
	global_store_dwordx4 v[176:177], v[180:183], off
	v_pk_fma_f32 v[176:177], v[4:5], v[160:161], v[92:93] op_sel_hi:[1,0,1]
	s_nop 0
	v_pk_fma_f32 v[182:183], v[6:7], v[160:161], v[94:95] op_sel_hi:[1,0,1]
	v_pk_fma_f32 v[180:181], v[8:9], v[160:161], v[96:97] op_sel_hi:[1,0,1]
	v_mul_f32_e32 v0, 0xbfb8aa3b, v182
	v_exp_f32_e32 v0, v0
	v_mul_f32_e32 v176, 0xbfb8aa3b, v176
	v_exp_f32_e32 v176, v176
	v_mul_f32_e32 v177, 0xbfb8aa3b, v177
	v_add_f32_e32 v0, 1.0, v0
	v_add_f32_e32 v176, 1.0, v176
	v_exp_f32_e32 v177, v177
	v_rcp_f32_e32 v0, v0
	s_nop 0
	v_mul_f32_e32 v169, 0xbfb8aa3b, v184
	v_exp_f32_e32 v169, v169
	v_add_f32_e32 v177, 1.0, v177
	v_add_f32_e32 v169, 1.0, v169
	v_rcp_f32_e32 v169, v169
	s_nop 0
	v_mul_f32_e32 v171, 0xbfb8aa3b, v183
	v_exp_f32_e32 v171, v171
	s_nop 0
	v_add_f32_e32 v171, 1.0, v171
	v_rcp_f32_e32 v171, v171
	s_nop 0
	v_mul_f32_e32 v173, 0xbfb8aa3b, v185
	v_exp_f32_e32 v173, v173
	s_nop 0
	v_add_f32_e32 v173, 1.0, v173
	v_rcp_f32_e32 v173, v173
	s_nop 0
	v_mul_f32_e32 v175, 0xbfb8aa3b, v180
	v_exp_f32_e32 v175, v175
	s_nop 0
	v_add_f32_e32 v175, 1.0, v175
	v_rcp_f32_e32 v175, v175
	s_nop 0
	v_rcp_f32_e32 v176, v176
	s_nop 0
	v_mul_f32_e32 v180, 0xbfb8aa3b, v181
	v_exp_f32_e32 v180, v180
	s_nop 0
	v_add_f32_e32 v180, 1.0, v180
	v_rcp_f32_e32 v181, v180
	s_nop 0
	s_mov_b64 s[2:3], 0
	v_rcp_f32_e32 v177, v177
	s_nop 0
	v_cvt_pk_bf16_f32 v180, v0, v171
	v_cvt_pk_bf16_f32 v181, v175, v181
	v_cvt_pk_bf16_f32 v182, v169, v173
	v_cvt_pk_bf16_f32 v183, v176, v177
	global_store_dwordx4 v[178:179], v[180:183], off offset:256

; __global__ void __launch_bounds__(NTHR, 2) mega_fwd(Params P0) {
	.amdhsa_kernel _Z8mega_fwd6Params
		.amdhsa_group_segment_fixed_size 0
		.amdhsa_private_segment_fixed_size 0
		.amdhsa_kernarg_size 528
		.amdhsa_user_sgpr_count 2
		.amdhsa_user_sgpr_dispatch_ptr 0
		.amdhsa_user_sgpr_queue_ptr 0
		.amdhsa_user_sgpr_kernarg_segment_ptr 1
		.amdhsa_user_sgpr_dispatch_id 0
		.amdhsa_user_sgpr_kernarg_preload_length 0
		.amdhsa_user_sgpr_kernarg_preload_offset 0
		.amdhsa_user_sgpr_private_segment_size 0
		.amdhsa_uses_dynamic_stack 0
		.amdhsa_enable_private_segment 0
		.amdhsa_system_sgpr_workgroup_id_x 1
		.amdhsa_system_sgpr_workgroup_id_y 0
		.amdhsa_system_sgpr_workgroup_id_z 0
		.amdhsa_system_sgpr_workgroup_info 0
		.amdhsa_system_vgpr_workitem_id 2
		.amdhsa_next_free_vgpr 256
		.amdhsa_next_free_sgpr 102
		.amdhsa_accum_offset 256
		.amdhsa_reserve_vcc 1
		.amdhsa_float_round_mode_32 0
		.amdhsa_float_round_mode_16_64 0
		.amdhsa_float_denorm_mode_32 3
		.amdhsa_float_denorm_mode_16_64 3
		.amdhsa_dx10_clamp 1
		.amdhsa_ieee_mode 1
		.amdhsa_fp16_overflow 0
		.amdhsa_tg_split 0
		.amdhsa_exception_fp_ieee_invalid_op 0
		.amdhsa_exception_fp_denorm_src 0
		.amdhsa_exception_fp_ieee_div_zero 0
		.amdhsa_exception_fp_ieee_overflow 0
		.amdhsa_exception_fp_ieee_underflow 0
		.amdhsa_exception_fp_ieee_inexact 0
		.amdhsa_exception_int_div_zero 0
	.end_amdhsa_kernel

; __global__ void __launch_bounds__(NTHR, 2) mega_fwd(Params P0) {
amdhsa.kernels:
  - .agpr_count:     0
    .args:
      - .offset:         0
        .size:           272
        .value_kind:     by_value
      - .offset:         272
        .size:           4
        .value_kind:     hidden_block_count_x
      - .offset:         276
        .size:           4
        .value_kind:     hidden_block_count_y
      - .offset:         280
        .size:           4
        .value_kind:     hidden_block_count_z
      - .offset:         284
        .size:           2
        .value_kind:     hidden_group_size_x
      - .offset:         286
        .size:           2
        .value_kind:     hidden_group_size_y
      - .offset:         288
        .size:           2
        .value_kind:     hidden_group_size_z
      - .offset:         290
        .size:           2
        .value_kind:     hidden_remainder_x
      - .offset:         292
        .size:           2
        .value_kind:     hidden_remainder_y
      - .offset:         294
        .size:           2
        .value_kind:     hidden_remainder_z
      - .offset:         312
        .size:           8
        .value_kind:     hidden_global_offset_x
      - .offset:         320
        .size:           8
        .value_kind:     hidden_global_offset_y
      - .offset:         328
        .size:           8
        .value_kind:     hidden_global_offset_z
      - .offset:         336
        .size:           2
        .value_kind:     hidden_grid_dims
      - .offset:         360
        .size:           8
        .value_kind:     hidden_multigrid_sync_arg
      - .offset:         392
        .size:           4
        .value_kind:     hidden_dynamic_lds_size
    .group_segment_fixed_size: 0
    .kernarg_segment_align: 8
    .kernarg_segment_size: 528
    .language:       OpenCL C
    .language_version:
      - 2
      - 0
    .max_flat_workgroup_size: 512
    .name:           _Z8mega_fwd6Params
    .private_segment_fixed_size: 0
    .sgpr_count:     108
    .sgpr_spill_count: 133
    .symbol:         _Z8mega_fwd6Params.kd
    .uniform_work_group_size: 1
    .uses_dynamic_stack: false
    .vgpr_count:     256
    .vgpr_spill_count: 0
    .wavefront_size: 64
